# hand-written PEER routing: unique-key rank via LDS broadcast, 8 heads unrolled
# speedup vs baseline: 1.1181x; 1.0573x over previous
.LBB0_1938:
	v_ashrrev_i32_e32 v103, 31, v102
	s_waitcnt vmcnt(5)
	v_lshrrev_b32_e32 v0, 19, v103
	v_add_u32_e32 v0, v102, v0
	v_ashrrev_i32_e32 v123, 13, v0
	v_readlane_b32 s0, v251, 44
	s_waitcnt vmcnt(0)
	v_lshlrev_b64 v[126:127], 10, v[102:103]
	v_lshl_add_u64 v[46:47], v[114:115], 0, v[126:127]
	v_add_u32_e32 v0, s0, v123
	s_movk_i32 s0, 0x1800
	v_mul_lo_u32 v16, v0, s0
	v_ashrrev_i32_e32 v17, 31, v16
	v_lshl_add_u64 v[128:129], v[16:17], 2, v[120:121]
	s_mov_b64 s[0:1], 0x4000
	v_lshl_add_u64 v[16:17], v[128:129], 0, s[0:1]
	s_mov_b64 s[0:1], 0x3000
	v_lshl_add_u64 v[18:19], v[128:129], 0, s[0:1]
	s_movk_i32 s0, 0x4000
	v_add_co_u32_e32 v28, vcc, s0, v128
	s_movk_i32 s0, 0x3000
	s_nop 0
	v_addc_co_u32_e32 v29, vcc, 0, v129, vcc
	v_lshlrev_b64 v[0:1], 12, v[102:103]
	v_add_co_u32_e32 v42, vcc, s0, v128
	v_lshl_add_u64 v[8:9], v[112:113], 0, v[0:1]
	s_nop 0
	v_addc_co_u32_e32 v43, vcc, 0, v129, vcc
	global_load_dwordx4 v[4:7], v[8:9], off offset:16
	global_load_dwordx4 v[0:3], v[8:9], off
	global_load_dwordx4 v[12:15], v[8:9], off offset:2064
	s_nop 0
	global_load_dwordx4 v[8:11], v[8:9], off offset:2048
	s_nop 0
	global_load_dwordx4 v[20:23], v[16:17], off offset:16
	global_load_dwordx4 v[24:27], v[18:19], off offset:16
	global_load_dwordx4 v[34:37], v[28:29], off
	s_nop 0
	global_load_dwordx4 v[28:31], v[28:29], off offset:2048
	s_nop 0
	global_load_dwordx4 v[38:41], v[42:43], off
	s_nop 0
	global_load_dwordx4 v[42:45], v[42:43], off offset:2048
	s_mov_b64 s[0:1], 0x4800
	v_lshl_add_u64 v[16:17], v[128:129], 0, s[0:1]
	s_mov_b64 s[0:1], 0x3800
	v_lshl_add_u64 v[18:19], v[128:129], 0, s[0:1]
	global_load_dwordx4 v[50:53], v[46:47], off
	s_nop 0
	global_load_dwordx4 v[46:49], v[16:17], off offset:16
	s_nop 0
	global_load_dwordx4 v[16:19], v[18:19], off offset:16
	v_writelane_b32 v253, s2, 26
	s_mov_b64 s[0:1], 0x800
	s_mov_b32 s14, 0
	v_writelane_b32 v253, s3, 27
	v_lshl_add_u64 v[130:131], v[128:129], 0, s[0:1]
	v_mov_b32_e32 v54, v174
	s_waitcnt vmcnt(2)
	ds_write_b128 v176, v[50:53]
	v_readfirstlane_b32 s0, v206
	s_lshr_b32 s0, s0, 6
	s_lshl_b32 s1, s0, 10
	s_add_u32 s1, s1, 0x2000
	s_lshl_b32 s2, s0, 12
	s_add_u32 s2, s2, 0x4000
	v_and_b32_e32 v55, 0xff, v178
	v_and_b32_e32 v56, 0xff, v179
	v_add_u32_e32 v55, s1, v55
	v_add_u32_e32 v56, s1, v56
	v_lshl_add_u32 v57, v214, 2, s2
	v_mov_b32_e32 v58, s2
	v_sub_u32_e32 v59, 63, v214
	v_lshl_add_u32 v101, v214, 3, s2
	v_add_u32_e32 v101, 0x800, v101
	s_mov_b32 s34, -1
	s_mov_b32 s35, 0x3ffff
	s_mov_b32 s36, 0xffffffc0
	ds_read_b32 v88, v55 offset:0
	ds_read_b32 v80, v56 offset:0
	ds_read_b32 v89, v55 offset:128
	ds_read_b32 v81, v56 offset:128
	ds_read_b32 v90, v55 offset:256
	ds_read_b32 v82, v56 offset:256
	ds_read_b32 v91, v55 offset:384
	ds_read_b32 v83, v56 offset:384
	ds_read_b32 v92, v55 offset:512
	ds_read_b32 v84, v56 offset:512
	ds_read_b32 v93, v55 offset:640
	ds_read_b32 v85, v56 offset:640
	ds_read_b32 v94, v55 offset:768
	ds_read_b32 v86, v56 offset:768
	ds_read_b32 v95, v55 offset:896
	ds_read_b32 v87, v56 offset:896
	s_waitcnt lgkmcnt(0)
	v_and_b32_e32 v61, 0xffffff80, v88
	v_and_b32_e32 v62, 0xffffff80, v80
	v_add_f32_e32 v64, v61, v62
	v_and_b32_e32 v61, 0x7f, v88
	v_and_b32_e32 v62, 0x7f, v80
	v_cndmask_b32_e64 v64, v222, v64, s[34:35]
	v_lshl_or_b32 v61, v61, 7, v62
	v_sub_u32_e32 v80, 0x3fff, v61
	v_ashrrev_i32_e32 v62, 31, v64
	v_or_b32_e32 v62, 0x80000000, v62
	v_xor_b32_e32 v62, v64, v62
	v_and_or_b32 v72, v62, s36, v59
	ds_write_b32 v57, v72 offset:0
	v_mov_b32_e32 v88, 0
	v_and_b32_e32 v61, 0xffffff80, v89
	v_and_b32_e32 v62, 0xffffff80, v81
	v_add_f32_e32 v65, v61, v62
	v_and_b32_e32 v61, 0x7f, v89
	v_and_b32_e32 v62, 0x7f, v81
	v_cndmask_b32_e64 v65, v222, v65, s[34:35]
	v_lshl_or_b32 v61, v61, 7, v62
	v_sub_u32_e32 v81, 0x3fff, v61
	v_ashrrev_i32_e32 v62, 31, v65
	v_or_b32_e32 v62, 0x80000000, v62
	v_xor_b32_e32 v62, v65, v62
	v_and_or_b32 v73, v62, s36, v59
	ds_write_b32 v57, v73 offset:256
	v_mov_b32_e32 v89, 0
	v_and_b32_e32 v61, 0xffffff80, v90
	v_and_b32_e32 v62, 0xffffff80, v82
	v_add_f32_e32 v66, v61, v62
	v_and_b32_e32 v61, 0x7f, v90
	v_and_b32_e32 v62, 0x7f, v82
	v_cndmask_b32_e64 v66, v222, v66, s[34:35]
	v_lshl_or_b32 v61, v61, 7, v62
	v_sub_u32_e32 v82, 0x3fff, v61
	v_ashrrev_i32_e32 v62, 31, v66
	v_or_b32_e32 v62, 0x80000000, v62
	v_xor_b32_e32 v62, v66, v62
	v_and_or_b32 v74, v62, s36, v59
	ds_write_b32 v57, v74 offset:512
	v_mov_b32_e32 v90, 0
	v_and_b32_e32 v61, 0xffffff80, v91
	v_and_b32_e32 v62, 0xffffff80, v83
	v_add_f32_e32 v67, v61, v62
	v_and_b32_e32 v61, 0x7f, v91
	v_and_b32_e32 v62, 0x7f, v83
	v_cndmask_b32_e64 v67, v222, v67, s[34:35]
	v_lshl_or_b32 v61, v61, 7, v62
	v_sub_u32_e32 v83, 0x3fff, v61
	v_ashrrev_i32_e32 v62, 31, v67
	v_or_b32_e32 v62, 0x80000000, v62
	v_xor_b32_e32 v62, v67, v62
	v_and_or_b32 v75, v62, s36, v59
	ds_write_b32 v57, v75 offset:768
	v_mov_b32_e32 v91, 0
	v_and_b32_e32 v61, 0xffffff80, v92
	v_and_b32_e32 v62, 0xffffff80, v84
	v_add_f32_e32 v68, v61, v62
	v_and_b32_e32 v61, 0x7f, v92
	v_and_b32_e32 v62, 0x7f, v84
	v_cndmask_b32_e64 v68, v222, v68, s[34:35]
	v_lshl_or_b32 v61, v61, 7, v62
	v_sub_u32_e32 v84, 0x3fff, v61
	v_ashrrev_i32_e32 v62, 31, v68
	v_or_b32_e32 v62, 0x80000000, v62
	v_xor_b32_e32 v62, v68, v62
	v_and_or_b32 v76, v62, s36, v59
	ds_write_b32 v57, v76 offset:1024
	v_mov_b32_e32 v92, 0
	v_and_b32_e32 v61, 0xffffff80, v93
	v_and_b32_e32 v62, 0xffffff80, v85
	v_add_f32_e32 v69, v61, v62
	v_and_b32_e32 v61, 0x7f, v93
	v_and_b32_e32 v62, 0x7f, v85
	v_cndmask_b32_e64 v69, v222, v69, s[34:35]
	v_lshl_or_b32 v61, v61, 7, v62
	v_sub_u32_e32 v85, 0x3fff, v61
	v_ashrrev_i32_e32 v62, 31, v69
	v_or_b32_e32 v62, 0x80000000, v62
	v_xor_b32_e32 v62, v69, v62
	v_and_or_b32 v77, v62, s36, v59
	ds_write_b32 v57, v77 offset:1280
	v_mov_b32_e32 v93, 0
	v_and_b32_e32 v61, 0xffffff80, v94
	v_and_b32_e32 v62, 0xffffff80, v86
	v_add_f32_e32 v70, v61, v62
	v_and_b32_e32 v61, 0x7f, v94
	v_and_b32_e32 v62, 0x7f, v86
	v_cndmask_b32_e64 v70, v222, v70, s[34:35]
	v_lshl_or_b32 v61, v61, 7, v62
	v_sub_u32_e32 v86, 0x3fff, v61
	v_ashrrev_i32_e32 v62, 31, v70
	v_or_b32_e32 v62, 0x80000000, v62
	v_xor_b32_e32 v62, v70, v62
	v_and_or_b32 v78, v62, s36, v59
	ds_write_b32 v57, v78 offset:1536
	v_mov_b32_e32 v94, 0
	v_and_b32_e32 v61, 0xffffff80, v95
	v_and_b32_e32 v62, 0xffffff80, v87
	v_add_f32_e32 v71, v61, v62
	v_and_b32_e32 v61, 0x7f, v95
	v_and_b32_e32 v62, 0x7f, v87
	v_cndmask_b32_e64 v71, v222, v71, s[34:35]
	v_lshl_or_b32 v61, v61, 7, v62
	v_sub_u32_e32 v87, 0x3fff, v61
	v_ashrrev_i32_e32 v62, 31, v71
	v_or_b32_e32 v62, 0x80000000, v62
	v_xor_b32_e32 v62, v71, v62
	v_and_or_b32 v79, v62, s36, v59
	ds_write_b32 v57, v79 offset:1792
	v_mov_b32_e32 v95, 0
	ds_read_b128 v[96:99], v58 offset:0
	ds_read_b128 v[60:63], v58 offset:16
	s_waitcnt lgkmcnt(1)
	v_cmp_gt_u32_e64 s[20:21], v96, v72
	v_cmp_gt_u32_e64 s[22:23], v97, v72
	v_cmp_gt_u32_e64 s[24:25], v98, v72
	v_addc_co_u32_e64 v88, s[30:31], 0, v88, s[20:21]
	v_cmp_gt_u32_e64 s[26:27], v99, v72
	v_addc_co_u32_e64 v88, s[30:31], 0, v88, s[22:23]
	ds_read_b128 v[96:99], v58 offset:32
	s_waitcnt lgkmcnt(1)
	v_cmp_gt_u32_e64 s[20:21], v60, v72
	v_addc_co_u32_e64 v88, s[30:31], 0, v88, s[24:25]
	v_cmp_gt_u32_e64 s[22:23], v61, v72
	v_addc_co_u32_e64 v88, s[30:31], 0, v88, s[26:27]
	v_cmp_gt_u32_e64 s[24:25], v62, v72
	v_addc_co_u32_e64 v88, s[30:31], 0, v88, s[20:21]
	v_cmp_gt_u32_e64 s[26:27], v63, v72
	v_addc_co_u32_e64 v88, s[30:31], 0, v88, s[22:23]
	ds_read_b128 v[60:63], v58 offset:48
	s_waitcnt lgkmcnt(1)
	v_cmp_gt_u32_e64 s[20:21], v96, v72
	v_addc_co_u32_e64 v88, s[30:31], 0, v88, s[24:25]
	v_cmp_gt_u32_e64 s[22:23], v97, v72
	v_addc_co_u32_e64 v88, s[30:31], 0, v88, s[26:27]
	v_cmp_gt_u32_e64 s[24:25], v98, v72
	v_addc_co_u32_e64 v88, s[30:31], 0, v88, s[20:21]
	v_cmp_gt_u32_e64 s[26:27], v99, v72
	v_addc_co_u32_e64 v88, s[30:31], 0, v88, s[22:23]
	ds_read_b128 v[96:99], v58 offset:64
	s_waitcnt lgkmcnt(1)
	v_cmp_gt_u32_e64 s[20:21], v60, v72
	v_addc_co_u32_e64 v88, s[30:31], 0, v88, s[24:25]
	v_cmp_gt_u32_e64 s[22:23], v61, v72
	v_addc_co_u32_e64 v88, s[30:31], 0, v88, s[26:27]
	v_cmp_gt_u32_e64 s[24:25], v62, v72
	v_addc_co_u32_e64 v88, s[30:31], 0, v88, s[20:21]
	v_cmp_gt_u32_e64 s[26:27], v63, v72
	v_addc_co_u32_e64 v88, s[30:31], 0, v88, s[22:23]
	ds_read_b128 v[60:63], v58 offset:80
	s_waitcnt lgkmcnt(1)
	v_cmp_gt_u32_e64 s[20:21], v96, v72
	v_addc_co_u32_e64 v88, s[30:31], 0, v88, s[24:25]
	v_cmp_gt_u32_e64 s[22:23], v97, v72
	v_addc_co_u32_e64 v88, s[30:31], 0, v88, s[26:27]
	v_cmp_gt_u32_e64 s[24:25], v98, v72
	v_addc_co_u32_e64 v88, s[30:31], 0, v88, s[20:21]
	v_cmp_gt_u32_e64 s[26:27], v99, v72
	v_addc_co_u32_e64 v88, s[30:31], 0, v88, s[22:23]
	ds_read_b128 v[96:99], v58 offset:96
	s_waitcnt lgkmcnt(1)
	v_cmp_gt_u32_e64 s[20:21], v60, v72
	v_addc_co_u32_e64 v88, s[30:31], 0, v88, s[24:25]
	v_cmp_gt_u32_e64 s[22:23], v61, v72
	v_addc_co_u32_e64 v88, s[30:31], 0, v88, s[26:27]
	v_cmp_gt_u32_e64 s[24:25], v62, v72
	v_addc_co_u32_e64 v88, s[30:31], 0, v88, s[20:21]
	v_cmp_gt_u32_e64 s[26:27], v63, v72
	v_addc_co_u32_e64 v88, s[30:31], 0, v88, s[22:23]
	ds_read_b128 v[60:63], v58 offset:112
	s_waitcnt lgkmcnt(1)
	v_cmp_gt_u32_e64 s[20:21], v96, v72
	v_addc_co_u32_e64 v88, s[30:31], 0, v88, s[24:25]
	v_cmp_gt_u32_e64 s[22:23], v97, v72
	v_addc_co_u32_e64 v88, s[30:31], 0, v88, s[26:27]
	v_cmp_gt_u32_e64 s[24:25], v98, v72
	v_addc_co_u32_e64 v88, s[30:31], 0, v88, s[20:21]
	v_cmp_gt_u32_e64 s[26:27], v99, v72
	v_addc_co_u32_e64 v88, s[30:31], 0, v88, s[22:23]
	ds_read_b128 v[96:99], v58 offset:128
	s_waitcnt lgkmcnt(1)
	v_cmp_gt_u32_e64 s[20:21], v60, v72
	v_addc_co_u32_e64 v88, s[30:31], 0, v88, s[24:25]
	v_cmp_gt_u32_e64 s[22:23], v61, v72
	v_addc_co_u32_e64 v88, s[30:31], 0, v88, s[26:27]
	v_cmp_gt_u32_e64 s[24:25], v62, v72
	v_addc_co_u32_e64 v88, s[30:31], 0, v88, s[20:21]
	v_cmp_gt_u32_e64 s[26:27], v63, v72
	v_addc_co_u32_e64 v88, s[30:31], 0, v88, s[22:23]
	ds_read_b128 v[60:63], v58 offset:144
	s_waitcnt lgkmcnt(1)
	v_cmp_gt_u32_e64 s[20:21], v96, v72
	v_addc_co_u32_e64 v88, s[30:31], 0, v88, s[24:25]
	v_cmp_gt_u32_e64 s[22:23], v97, v72
	v_addc_co_u32_e64 v88, s[30:31], 0, v88, s[26:27]
	v_cmp_gt_u32_e64 s[24:25], v98, v72
	v_addc_co_u32_e64 v88, s[30:31], 0, v88, s[20:21]
	v_cmp_gt_u32_e64 s[26:27], v99, v72
	v_addc_co_u32_e64 v88, s[30:31], 0, v88, s[22:23]
	ds_read_b128 v[96:99], v58 offset:160
	s_waitcnt lgkmcnt(1)
	v_cmp_gt_u32_e64 s[20:21], v60, v72
	v_addc_co_u32_e64 v88, s[30:31], 0, v88, s[24:25]
	v_cmp_gt_u32_e64 s[22:23], v61, v72
	v_addc_co_u32_e64 v88, s[30:31], 0, v88, s[26:27]
	v_cmp_gt_u32_e64 s[24:25], v62, v72
	v_addc_co_u32_e64 v88, s[30:31], 0, v88, s[20:21]
	v_cmp_gt_u32_e64 s[26:27], v63, v72
	v_addc_co_u32_e64 v88, s[30:31], 0, v88, s[22:23]
	ds_read_b128 v[60:63], v58 offset:176
	s_waitcnt lgkmcnt(1)
	v_cmp_gt_u32_e64 s[20:21], v96, v72
	v_addc_co_u32_e64 v88, s[30:31], 0, v88, s[24:25]
	v_cmp_gt_u32_e64 s[22:23], v97, v72
	v_addc_co_u32_e64 v88, s[30:31], 0, v88, s[26:27]
	v_cmp_gt_u32_e64 s[24:25], v98, v72
	v_addc_co_u32_e64 v88, s[30:31], 0, v88, s[20:21]
	v_cmp_gt_u32_e64 s[26:27], v99, v72
	v_addc_co_u32_e64 v88, s[30:31], 0, v88, s[22:23]
	ds_read_b128 v[96:99], v58 offset:192
	s_waitcnt lgkmcnt(1)
	v_cmp_gt_u32_e64 s[20:21], v60, v72
	v_addc_co_u32_e64 v88, s[30:31], 0, v88, s[24:25]
	v_cmp_gt_u32_e64 s[22:23], v61, v72
	v_addc_co_u32_e64 v88, s[30:31], 0, v88, s[26:27]
	v_cmp_gt_u32_e64 s[24:25], v62, v72
	v_addc_co_u32_e64 v88, s[30:31], 0, v88, s[20:21]
	v_cmp_gt_u32_e64 s[26:27], v63, v72
	v_addc_co_u32_e64 v88, s[30:31], 0, v88, s[22:23]
	s_waitcnt lgkmcnt(0)
	v_cmp_gt_u32_e64 s[20:21], v96, v72
	v_addc_co_u32_e64 v88, s[30:31], 0, v88, s[24:25]
	v_cmp_gt_u32_e64 s[22:23], v97, v72
	v_addc_co_u32_e64 v88, s[30:31], 0, v88, s[26:27]
	v_addc_co_u32_e64 v88, s[30:31], 0, v88, s[20:21]
	s_nop 1
	v_addc_co_u32_e64 v88, s[30:31], 0, v88, s[22:23]
	ds_read_b128 v[96:99], v58 offset:256
	ds_read_b128 v[60:63], v58 offset:272
	s_waitcnt lgkmcnt(1)
	v_cmp_gt_u32_e64 s[20:21], v96, v73
	v_cmp_gt_u32_e64 s[22:23], v97, v73
	v_cmp_gt_u32_e64 s[24:25], v98, v73
	v_addc_co_u32_e64 v89, s[30:31], 0, v89, s[20:21]
	v_cmp_gt_u32_e64 s[26:27], v99, v73
	v_addc_co_u32_e64 v89, s[30:31], 0, v89, s[22:23]
	ds_read_b128 v[96:99], v58 offset:288
	s_waitcnt lgkmcnt(1)
	v_cmp_gt_u32_e64 s[20:21], v60, v73
	v_addc_co_u32_e64 v89, s[30:31], 0, v89, s[24:25]
	v_cmp_gt_u32_e64 s[22:23], v61, v73
	v_addc_co_u32_e64 v89, s[30:31], 0, v89, s[26:27]
	v_cmp_gt_u32_e64 s[24:25], v62, v73
	v_addc_co_u32_e64 v89, s[30:31], 0, v89, s[20:21]
	v_cmp_gt_u32_e64 s[26:27], v63, v73
	v_addc_co_u32_e64 v89, s[30:31], 0, v89, s[22:23]
	ds_read_b128 v[60:63], v58 offset:304
	s_waitcnt lgkmcnt(1)
	v_cmp_gt_u32_e64 s[20:21], v96, v73
	v_addc_co_u32_e64 v89, s[30:31], 0, v89, s[24:25]
	v_cmp_gt_u32_e64 s[22:23], v97, v73
	v_addc_co_u32_e64 v89, s[30:31], 0, v89, s[26:27]
	v_cmp_gt_u32_e64 s[24:25], v98, v73
	v_addc_co_u32_e64 v89, s[30:31], 0, v89, s[20:21]
	v_cmp_gt_u32_e64 s[26:27], v99, v73
	v_addc_co_u32_e64 v89, s[30:31], 0, v89, s[22:23]
	ds_read_b128 v[96:99], v58 offset:320
	s_waitcnt lgkmcnt(1)
	v_cmp_gt_u32_e64 s[20:21], v60, v73
	v_addc_co_u32_e64 v89, s[30:31], 0, v89, s[24:25]
	v_cmp_gt_u32_e64 s[22:23], v61, v73
	v_addc_co_u32_e64 v89, s[30:31], 0, v89, s[26:27]
	v_cmp_gt_u32_e64 s[24:25], v62, v73
	v_addc_co_u32_e64 v89, s[30:31], 0, v89, s[20:21]
	v_cmp_gt_u32_e64 s[26:27], v63, v73
	v_addc_co_u32_e64 v89, s[30:31], 0, v89, s[22:23]
	ds_read_b128 v[60:63], v58 offset:336
	s_waitcnt lgkmcnt(1)
	v_cmp_gt_u32_e64 s[20:21], v96, v73
	v_addc_co_u32_e64 v89, s[30:31], 0, v89, s[24:25]
	v_cmp_gt_u32_e64 s[22:23], v97, v73
	v_addc_co_u32_e64 v89, s[30:31], 0, v89, s[26:27]
	v_cmp_gt_u32_e64 s[24:25], v98, v73
	v_addc_co_u32_e64 v89, s[30:31], 0, v89, s[20:21]
	v_cmp_gt_u32_e64 s[26:27], v99, v73
	v_addc_co_u32_e64 v89, s[30:31], 0, v89, s[22:23]
	ds_read_b128 v[96:99], v58 offset:352
	s_waitcnt lgkmcnt(1)
	v_cmp_gt_u32_e64 s[20:21], v60, v73
	v_addc_co_u32_e64 v89, s[30:31], 0, v89, s[24:25]
	v_cmp_gt_u32_e64 s[22:23], v61, v73
	v_addc_co_u32_e64 v89, s[30:31], 0, v89, s[26:27]
	v_cmp_gt_u32_e64 s[24:25], v62, v73
	v_addc_co_u32_e64 v89, s[30:31], 0, v89, s[20:21]
	v_cmp_gt_u32_e64 s[26:27], v63, v73
	v_addc_co_u32_e64 v89, s[30:31], 0, v89, s[22:23]
	ds_read_b128 v[60:63], v58 offset:368
	s_waitcnt lgkmcnt(1)
	v_cmp_gt_u32_e64 s[20:21], v96, v73
	v_addc_co_u32_e64 v89, s[30:31], 0, v89, s[24:25]
	v_cmp_gt_u32_e64 s[22:23], v97, v73
	v_addc_co_u32_e64 v89, s[30:31], 0, v89, s[26:27]
	v_cmp_gt_u32_e64 s[24:25], v98, v73
	v_addc_co_u32_e64 v89, s[30:31], 0, v89, s[20:21]
	v_cmp_gt_u32_e64 s[26:27], v99, v73
	v_addc_co_u32_e64 v89, s[30:31], 0, v89, s[22:23]
	ds_read_b128 v[96:99], v58 offset:384
	s_waitcnt lgkmcnt(1)
	v_cmp_gt_u32_e64 s[20:21], v60, v73
	v_addc_co_u32_e64 v89, s[30:31], 0, v89, s[24:25]
	v_cmp_gt_u32_e64 s[22:23], v61, v73
	v_addc_co_u32_e64 v89, s[30:31], 0, v89, s[26:27]
	v_cmp_gt_u32_e64 s[24:25], v62, v73
	v_addc_co_u32_e64 v89, s[30:31], 0, v89, s[20:21]
	v_cmp_gt_u32_e64 s[26:27], v63, v73
	v_addc_co_u32_e64 v89, s[30:31], 0, v89, s[22:23]
	ds_read_b128 v[60:63], v58 offset:400
	s_waitcnt lgkmcnt(1)
	v_cmp_gt_u32_e64 s[20:21], v96, v73
	v_addc_co_u32_e64 v89, s[30:31], 0, v89, s[24:25]
	v_cmp_gt_u32_e64 s[22:23], v97, v73
	v_addc_co_u32_e64 v89, s[30:31], 0, v89, s[26:27]
	v_cmp_gt_u32_e64 s[24:25], v98, v73
	v_addc_co_u32_e64 v89, s[30:31], 0, v89, s[20:21]
	v_cmp_gt_u32_e64 s[26:27], v99, v73
	v_addc_co_u32_e64 v89, s[30:31], 0, v89, s[22:23]
	ds_read_b128 v[96:99], v58 offset:416
	s_waitcnt lgkmcnt(1)
	v_cmp_gt_u32_e64 s[20:21], v60, v73
	v_addc_co_u32_e64 v89, s[30:31], 0, v89, s[24:25]
	v_cmp_gt_u32_e64 s[22:23], v61, v73
	v_addc_co_u32_e64 v89, s[30:31], 0, v89, s[26:27]
	v_cmp_gt_u32_e64 s[24:25], v62, v73
	v_addc_co_u32_e64 v89, s[30:31], 0, v89, s[20:21]
	v_cmp_gt_u32_e64 s[26:27], v63, v73
	v_addc_co_u32_e64 v89, s[30:31], 0, v89, s[22:23]
	ds_read_b128 v[60:63], v58 offset:432
	s_waitcnt lgkmcnt(1)
	v_cmp_gt_u32_e64 s[20:21], v96, v73
	v_addc_co_u32_e64 v89, s[30:31], 0, v89, s[24:25]
	v_cmp_gt_u32_e64 s[22:23], v97, v73
	v_addc_co_u32_e64 v89, s[30:31], 0, v89, s[26:27]
	v_cmp_gt_u32_e64 s[24:25], v98, v73
	v_addc_co_u32_e64 v89, s[30:31], 0, v89, s[20:21]
	v_cmp_gt_u32_e64 s[26:27], v99, v73
	v_addc_co_u32_e64 v89, s[30:31], 0, v89, s[22:23]
	ds_read_b128 v[96:99], v58 offset:448
	s_waitcnt lgkmcnt(1)
	v_cmp_gt_u32_e64 s[20:21], v60, v73
	v_addc_co_u32_e64 v89, s[30:31], 0, v89, s[24:25]
	v_cmp_gt_u32_e64 s[22:23], v61, v73
	v_addc_co_u32_e64 v89, s[30:31], 0, v89, s[26:27]
	v_cmp_gt_u32_e64 s[24:25], v62, v73
	v_addc_co_u32_e64 v89, s[30:31], 0, v89, s[20:21]
	v_cmp_gt_u32_e64 s[26:27], v63, v73
	v_addc_co_u32_e64 v89, s[30:31], 0, v89, s[22:23]
	s_waitcnt lgkmcnt(0)
	v_cmp_gt_u32_e64 s[20:21], v96, v73
	v_addc_co_u32_e64 v89, s[30:31], 0, v89, s[24:25]
	v_cmp_gt_u32_e64 s[22:23], v97, v73
	v_addc_co_u32_e64 v89, s[30:31], 0, v89, s[26:27]
	v_addc_co_u32_e64 v89, s[30:31], 0, v89, s[20:21]
	s_nop 1
	v_addc_co_u32_e64 v89, s[30:31], 0, v89, s[22:23]
	ds_read_b128 v[96:99], v58 offset:512
	ds_read_b128 v[60:63], v58 offset:528
	s_waitcnt lgkmcnt(1)
	v_cmp_gt_u32_e64 s[20:21], v96, v74
	v_cmp_gt_u32_e64 s[22:23], v97, v74
	v_cmp_gt_u32_e64 s[24:25], v98, v74
	v_addc_co_u32_e64 v90, s[30:31], 0, v90, s[20:21]
	v_cmp_gt_u32_e64 s[26:27], v99, v74
	v_addc_co_u32_e64 v90, s[30:31], 0, v90, s[22:23]
	ds_read_b128 v[96:99], v58 offset:544
	s_waitcnt lgkmcnt(1)
	v_cmp_gt_u32_e64 s[20:21], v60, v74
	v_addc_co_u32_e64 v90, s[30:31], 0, v90, s[24:25]
	v_cmp_gt_u32_e64 s[22:23], v61, v74
	v_addc_co_u32_e64 v90, s[30:31], 0, v90, s[26:27]
	v_cmp_gt_u32_e64 s[24:25], v62, v74
	v_addc_co_u32_e64 v90, s[30:31], 0, v90, s[20:21]
	v_cmp_gt_u32_e64 s[26:27], v63, v74
	v_addc_co_u32_e64 v90, s[30:31], 0, v90, s[22:23]
	ds_read_b128 v[60:63], v58 offset:560
	s_waitcnt lgkmcnt(1)
	v_cmp_gt_u32_e64 s[20:21], v96, v74
	v_addc_co_u32_e64 v90, s[30:31], 0, v90, s[24:25]
	v_cmp_gt_u32_e64 s[22:23], v97, v74
	v_addc_co_u32_e64 v90, s[30:31], 0, v90, s[26:27]
	v_cmp_gt_u32_e64 s[24:25], v98, v74
	v_addc_co_u32_e64 v90, s[30:31], 0, v90, s[20:21]
	v_cmp_gt_u32_e64 s[26:27], v99, v74
	v_addc_co_u32_e64 v90, s[30:31], 0, v90, s[22:23]
	ds_read_b128 v[96:99], v58 offset:576
	s_waitcnt lgkmcnt(1)
	v_cmp_gt_u32_e64 s[20:21], v60, v74
	v_addc_co_u32_e64 v90, s[30:31], 0, v90, s[24:25]
	v_cmp_gt_u32_e64 s[22:23], v61, v74
	v_addc_co_u32_e64 v90, s[30:31], 0, v90, s[26:27]
	v_cmp_gt_u32_e64 s[24:25], v62, v74
	v_addc_co_u32_e64 v90, s[30:31], 0, v90, s[20:21]
	v_cmp_gt_u32_e64 s[26:27], v63, v74
	v_addc_co_u32_e64 v90, s[30:31], 0, v90, s[22:23]
	ds_read_b128 v[60:63], v58 offset:592
	s_waitcnt lgkmcnt(1)
	v_cmp_gt_u32_e64 s[20:21], v96, v74
	v_addc_co_u32_e64 v90, s[30:31], 0, v90, s[24:25]
	v_cmp_gt_u32_e64 s[22:23], v97, v74
	v_addc_co_u32_e64 v90, s[30:31], 0, v90, s[26:27]
	v_cmp_gt_u32_e64 s[24:25], v98, v74
	v_addc_co_u32_e64 v90, s[30:31], 0, v90, s[20:21]
	v_cmp_gt_u32_e64 s[26:27], v99, v74
	v_addc_co_u32_e64 v90, s[30:31], 0, v90, s[22:23]
	ds_read_b128 v[96:99], v58 offset:608
	s_waitcnt lgkmcnt(1)
	v_cmp_gt_u32_e64 s[20:21], v60, v74
	v_addc_co_u32_e64 v90, s[30:31], 0, v90, s[24:25]
	v_cmp_gt_u32_e64 s[22:23], v61, v74
	v_addc_co_u32_e64 v90, s[30:31], 0, v90, s[26:27]
	v_cmp_gt_u32_e64 s[24:25], v62, v74
	v_addc_co_u32_e64 v90, s[30:31], 0, v90, s[20:21]
	v_cmp_gt_u32_e64 s[26:27], v63, v74
	v_addc_co_u32_e64 v90, s[30:31], 0, v90, s[22:23]
	ds_read_b128 v[60:63], v58 offset:624
	s_waitcnt lgkmcnt(1)
	v_cmp_gt_u32_e64 s[20:21], v96, v74
	v_addc_co_u32_e64 v90, s[30:31], 0, v90, s[24:25]
	v_cmp_gt_u32_e64 s[22:23], v97, v74
	v_addc_co_u32_e64 v90, s[30:31], 0, v90, s[26:27]
	v_cmp_gt_u32_e64 s[24:25], v98, v74
	v_addc_co_u32_e64 v90, s[30:31], 0, v90, s[20:21]
	v_cmp_gt_u32_e64 s[26:27], v99, v74
	v_addc_co_u32_e64 v90, s[30:31], 0, v90, s[22:23]
	ds_read_b128 v[96:99], v58 offset:640
	s_waitcnt lgkmcnt(1)
	v_cmp_gt_u32_e64 s[20:21], v60, v74
	v_addc_co_u32_e64 v90, s[30:31], 0, v90, s[24:25]
	v_cmp_gt_u32_e64 s[22:23], v61, v74
	v_addc_co_u32_e64 v90, s[30:31], 0, v90, s[26:27]
	v_cmp_gt_u32_e64 s[24:25], v62, v74
	v_addc_co_u32_e64 v90, s[30:31], 0, v90, s[20:21]
	v_cmp_gt_u32_e64 s[26:27], v63, v74
	v_addc_co_u32_e64 v90, s[30:31], 0, v90, s[22:23]
	ds_read_b128 v[60:63], v58 offset:656
	s_waitcnt lgkmcnt(1)
	v_cmp_gt_u32_e64 s[20:21], v96, v74
	v_addc_co_u32_e64 v90, s[30:31], 0, v90, s[24:25]
	v_cmp_gt_u32_e64 s[22:23], v97, v74
	v_addc_co_u32_e64 v90, s[30:31], 0, v90, s[26:27]
	v_cmp_gt_u32_e64 s[24:25], v98, v74
	v_addc_co_u32_e64 v90, s[30:31], 0, v90, s[20:21]
	v_cmp_gt_u32_e64 s[26:27], v99, v74
	v_addc_co_u32_e64 v90, s[30:31], 0, v90, s[22:23]
	ds_read_b128 v[96:99], v58 offset:672
	s_waitcnt lgkmcnt(1)
	v_cmp_gt_u32_e64 s[20:21], v60, v74
	v_addc_co_u32_e64 v90, s[30:31], 0, v90, s[24:25]
	v_cmp_gt_u32_e64 s[22:23], v61, v74
	v_addc_co_u32_e64 v90, s[30:31], 0, v90, s[26:27]
	v_cmp_gt_u32_e64 s[24:25], v62, v74
	v_addc_co_u32_e64 v90, s[30:31], 0, v90, s[20:21]
	v_cmp_gt_u32_e64 s[26:27], v63, v74
	v_addc_co_u32_e64 v90, s[30:31], 0, v90, s[22:23]
	ds_read_b128 v[60:63], v58 offset:688
	s_waitcnt lgkmcnt(1)
	v_cmp_gt_u32_e64 s[20:21], v96, v74
	v_addc_co_u32_e64 v90, s[30:31], 0, v90, s[24:25]
	v_cmp_gt_u32_e64 s[22:23], v97, v74
	v_addc_co_u32_e64 v90, s[30:31], 0, v90, s[26:27]
	v_cmp_gt_u32_e64 s[24:25], v98, v74
	v_addc_co_u32_e64 v90, s[30:31], 0, v90, s[20:21]
	v_cmp_gt_u32_e64 s[26:27], v99, v74
	v_addc_co_u32_e64 v90, s[30:31], 0, v90, s[22:23]
	ds_read_b128 v[96:99], v58 offset:704
	s_waitcnt lgkmcnt(1)
	v_cmp_gt_u32_e64 s[20:21], v60, v74
	v_addc_co_u32_e64 v90, s[30:31], 0, v90, s[24:25]
	v_cmp_gt_u32_e64 s[22:23], v61, v74
	v_addc_co_u32_e64 v90, s[30:31], 0, v90, s[26:27]
	v_cmp_gt_u32_e64 s[24:25], v62, v74
	v_addc_co_u32_e64 v90, s[30:31], 0, v90, s[20:21]
	v_cmp_gt_u32_e64 s[26:27], v63, v74
	v_addc_co_u32_e64 v90, s[30:31], 0, v90, s[22:23]
	s_waitcnt lgkmcnt(0)
	v_cmp_gt_u32_e64 s[20:21], v96, v74
	v_addc_co_u32_e64 v90, s[30:31], 0, v90, s[24:25]
	v_cmp_gt_u32_e64 s[22:23], v97, v74
	v_addc_co_u32_e64 v90, s[30:31], 0, v90, s[26:27]
	v_addc_co_u32_e64 v90, s[30:31], 0, v90, s[20:21]
	s_nop 1
	v_addc_co_u32_e64 v90, s[30:31], 0, v90, s[22:23]
	ds_read_b128 v[96:99], v58 offset:768
	ds_read_b128 v[60:63], v58 offset:784
	s_waitcnt lgkmcnt(1)
	v_cmp_gt_u32_e64 s[20:21], v96, v75
	v_cmp_gt_u32_e64 s[22:23], v97, v75
	v_cmp_gt_u32_e64 s[24:25], v98, v75
	v_addc_co_u32_e64 v91, s[30:31], 0, v91, s[20:21]
	v_cmp_gt_u32_e64 s[26:27], v99, v75
	v_addc_co_u32_e64 v91, s[30:31], 0, v91, s[22:23]
	ds_read_b128 v[96:99], v58 offset:800
	s_waitcnt lgkmcnt(1)
	v_cmp_gt_u32_e64 s[20:21], v60, v75
	v_addc_co_u32_e64 v91, s[30:31], 0, v91, s[24:25]
	v_cmp_gt_u32_e64 s[22:23], v61, v75
	v_addc_co_u32_e64 v91, s[30:31], 0, v91, s[26:27]
	v_cmp_gt_u32_e64 s[24:25], v62, v75
	v_addc_co_u32_e64 v91, s[30:31], 0, v91, s[20:21]
	v_cmp_gt_u32_e64 s[26:27], v63, v75
	v_addc_co_u32_e64 v91, s[30:31], 0, v91, s[22:23]
	ds_read_b128 v[60:63], v58 offset:816
	s_waitcnt lgkmcnt(1)
	v_cmp_gt_u32_e64 s[20:21], v96, v75
	v_addc_co_u32_e64 v91, s[30:31], 0, v91, s[24:25]
	v_cmp_gt_u32_e64 s[22:23], v97, v75
	v_addc_co_u32_e64 v91, s[30:31], 0, v91, s[26:27]
	v_cmp_gt_u32_e64 s[24:25], v98, v75
	v_addc_co_u32_e64 v91, s[30:31], 0, v91, s[20:21]
	v_cmp_gt_u32_e64 s[26:27], v99, v75
	v_addc_co_u32_e64 v91, s[30:31], 0, v91, s[22:23]
	ds_read_b128 v[96:99], v58 offset:832
	s_waitcnt lgkmcnt(1)
	v_cmp_gt_u32_e64 s[20:21], v60, v75
	v_addc_co_u32_e64 v91, s[30:31], 0, v91, s[24:25]
	v_cmp_gt_u32_e64 s[22:23], v61, v75
	v_addc_co_u32_e64 v91, s[30:31], 0, v91, s[26:27]
	v_cmp_gt_u32_e64 s[24:25], v62, v75
	v_addc_co_u32_e64 v91, s[30:31], 0, v91, s[20:21]
	v_cmp_gt_u32_e64 s[26:27], v63, v75
	v_addc_co_u32_e64 v91, s[30:31], 0, v91, s[22:23]
	ds_read_b128 v[60:63], v58 offset:848
	s_waitcnt lgkmcnt(1)
	v_cmp_gt_u32_e64 s[20:21], v96, v75
	v_addc_co_u32_e64 v91, s[30:31], 0, v91, s[24:25]
	v_cmp_gt_u32_e64 s[22:23], v97, v75
	v_addc_co_u32_e64 v91, s[30:31], 0, v91, s[26:27]
	v_cmp_gt_u32_e64 s[24:25], v98, v75
	v_addc_co_u32_e64 v91, s[30:31], 0, v91, s[20:21]
	v_cmp_gt_u32_e64 s[26:27], v99, v75
	v_addc_co_u32_e64 v91, s[30:31], 0, v91, s[22:23]
	ds_read_b128 v[96:99], v58 offset:864
	s_waitcnt lgkmcnt(1)
	v_cmp_gt_u32_e64 s[20:21], v60, v75
	v_addc_co_u32_e64 v91, s[30:31], 0, v91, s[24:25]
	v_cmp_gt_u32_e64 s[22:23], v61, v75
	v_addc_co_u32_e64 v91, s[30:31], 0, v91, s[26:27]
	v_cmp_gt_u32_e64 s[24:25], v62, v75
	v_addc_co_u32_e64 v91, s[30:31], 0, v91, s[20:21]
	v_cmp_gt_u32_e64 s[26:27], v63, v75
	v_addc_co_u32_e64 v91, s[30:31], 0, v91, s[22:23]
	ds_read_b128 v[60:63], v58 offset:880
	s_waitcnt lgkmcnt(1)
	v_cmp_gt_u32_e64 s[20:21], v96, v75
	v_addc_co_u32_e64 v91, s[30:31], 0, v91, s[24:25]
	v_cmp_gt_u32_e64 s[22:23], v97, v75
	v_addc_co_u32_e64 v91, s[30:31], 0, v91, s[26:27]
	v_cmp_gt_u32_e64 s[24:25], v98, v75
	v_addc_co_u32_e64 v91, s[30:31], 0, v91, s[20:21]
	v_cmp_gt_u32_e64 s[26:27], v99, v75
	v_addc_co_u32_e64 v91, s[30:31], 0, v91, s[22:23]
	ds_read_b128 v[96:99], v58 offset:896
	s_waitcnt lgkmcnt(1)
	v_cmp_gt_u32_e64 s[20:21], v60, v75
	v_addc_co_u32_e64 v91, s[30:31], 0, v91, s[24:25]
	v_cmp_gt_u32_e64 s[22:23], v61, v75
	v_addc_co_u32_e64 v91, s[30:31], 0, v91, s[26:27]
	v_cmp_gt_u32_e64 s[24:25], v62, v75
	v_addc_co_u32_e64 v91, s[30:31], 0, v91, s[20:21]
	v_cmp_gt_u32_e64 s[26:27], v63, v75
	v_addc_co_u32_e64 v91, s[30:31], 0, v91, s[22:23]
	ds_read_b128 v[60:63], v58 offset:912
	s_waitcnt lgkmcnt(1)
	v_cmp_gt_u32_e64 s[20:21], v96, v75
	v_addc_co_u32_e64 v91, s[30:31], 0, v91, s[24:25]
	v_cmp_gt_u32_e64 s[22:23], v97, v75
	v_addc_co_u32_e64 v91, s[30:31], 0, v91, s[26:27]
	v_cmp_gt_u32_e64 s[24:25], v98, v75
	v_addc_co_u32_e64 v91, s[30:31], 0, v91, s[20:21]
	v_cmp_gt_u32_e64 s[26:27], v99, v75
	v_addc_co_u32_e64 v91, s[30:31], 0, v91, s[22:23]
	ds_read_b128 v[96:99], v58 offset:928
	s_waitcnt lgkmcnt(1)
	v_cmp_gt_u32_e64 s[20:21], v60, v75
	v_addc_co_u32_e64 v91, s[30:31], 0, v91, s[24:25]
	v_cmp_gt_u32_e64 s[22:23], v61, v75
	v_addc_co_u32_e64 v91, s[30:31], 0, v91, s[26:27]
	v_cmp_gt_u32_e64 s[24:25], v62, v75
	v_addc_co_u32_e64 v91, s[30:31], 0, v91, s[20:21]
	v_cmp_gt_u32_e64 s[26:27], v63, v75
	v_addc_co_u32_e64 v91, s[30:31], 0, v91, s[22:23]
	ds_read_b128 v[60:63], v58 offset:944
	s_waitcnt lgkmcnt(1)
	v_cmp_gt_u32_e64 s[20:21], v96, v75
	v_addc_co_u32_e64 v91, s[30:31], 0, v91, s[24:25]
	v_cmp_gt_u32_e64 s[22:23], v97, v75
	v_addc_co_u32_e64 v91, s[30:31], 0, v91, s[26:27]
	v_cmp_gt_u32_e64 s[24:25], v98, v75
	v_addc_co_u32_e64 v91, s[30:31], 0, v91, s[20:21]
	v_cmp_gt_u32_e64 s[26:27], v99, v75
	v_addc_co_u32_e64 v91, s[30:31], 0, v91, s[22:23]
	ds_read_b128 v[96:99], v58 offset:960
	s_waitcnt lgkmcnt(1)
	v_cmp_gt_u32_e64 s[20:21], v60, v75
	v_addc_co_u32_e64 v91, s[30:31], 0, v91, s[24:25]
	v_cmp_gt_u32_e64 s[22:23], v61, v75
	v_addc_co_u32_e64 v91, s[30:31], 0, v91, s[26:27]
	v_cmp_gt_u32_e64 s[24:25], v62, v75
	v_addc_co_u32_e64 v91, s[30:31], 0, v91, s[20:21]
	v_cmp_gt_u32_e64 s[26:27], v63, v75
	v_addc_co_u32_e64 v91, s[30:31], 0, v91, s[22:23]
	s_waitcnt lgkmcnt(0)
	v_cmp_gt_u32_e64 s[20:21], v96, v75
	v_addc_co_u32_e64 v91, s[30:31], 0, v91, s[24:25]
	v_cmp_gt_u32_e64 s[22:23], v97, v75
	v_addc_co_u32_e64 v91, s[30:31], 0, v91, s[26:27]
	v_addc_co_u32_e64 v91, s[30:31], 0, v91, s[20:21]
	s_nop 1
	v_addc_co_u32_e64 v91, s[30:31], 0, v91, s[22:23]
	ds_read_b128 v[96:99], v58 offset:1024
	ds_read_b128 v[60:63], v58 offset:1040
	s_waitcnt lgkmcnt(1)
	v_cmp_gt_u32_e64 s[20:21], v96, v76
	v_cmp_gt_u32_e64 s[22:23], v97, v76
	v_cmp_gt_u32_e64 s[24:25], v98, v76
	v_addc_co_u32_e64 v92, s[30:31], 0, v92, s[20:21]
	v_cmp_gt_u32_e64 s[26:27], v99, v76
	v_addc_co_u32_e64 v92, s[30:31], 0, v92, s[22:23]
	ds_read_b128 v[96:99], v58 offset:1056
	s_waitcnt lgkmcnt(1)
	v_cmp_gt_u32_e64 s[20:21], v60, v76
	v_addc_co_u32_e64 v92, s[30:31], 0, v92, s[24:25]
	v_cmp_gt_u32_e64 s[22:23], v61, v76
	v_addc_co_u32_e64 v92, s[30:31], 0, v92, s[26:27]
	v_cmp_gt_u32_e64 s[24:25], v62, v76
	v_addc_co_u32_e64 v92, s[30:31], 0, v92, s[20:21]
	v_cmp_gt_u32_e64 s[26:27], v63, v76
	v_addc_co_u32_e64 v92, s[30:31], 0, v92, s[22:23]
	ds_read_b128 v[60:63], v58 offset:1072
	s_waitcnt lgkmcnt(1)
	v_cmp_gt_u32_e64 s[20:21], v96, v76
	v_addc_co_u32_e64 v92, s[30:31], 0, v92, s[24:25]
	v_cmp_gt_u32_e64 s[22:23], v97, v76
	v_addc_co_u32_e64 v92, s[30:31], 0, v92, s[26:27]
	v_cmp_gt_u32_e64 s[24:25], v98, v76
	v_addc_co_u32_e64 v92, s[30:31], 0, v92, s[20:21]
	v_cmp_gt_u32_e64 s[26:27], v99, v76
	v_addc_co_u32_e64 v92, s[30:31], 0, v92, s[22:23]
	ds_read_b128 v[96:99], v58 offset:1088
	s_waitcnt lgkmcnt(1)
	v_cmp_gt_u32_e64 s[20:21], v60, v76
	v_addc_co_u32_e64 v92, s[30:31], 0, v92, s[24:25]
	v_cmp_gt_u32_e64 s[22:23], v61, v76
	v_addc_co_u32_e64 v92, s[30:31], 0, v92, s[26:27]
	v_cmp_gt_u32_e64 s[24:25], v62, v76
	v_addc_co_u32_e64 v92, s[30:31], 0, v92, s[20:21]
	v_cmp_gt_u32_e64 s[26:27], v63, v76
	v_addc_co_u32_e64 v92, s[30:31], 0, v92, s[22:23]
	ds_read_b128 v[60:63], v58 offset:1104
	s_waitcnt lgkmcnt(1)
	v_cmp_gt_u32_e64 s[20:21], v96, v76
	v_addc_co_u32_e64 v92, s[30:31], 0, v92, s[24:25]
	v_cmp_gt_u32_e64 s[22:23], v97, v76
	v_addc_co_u32_e64 v92, s[30:31], 0, v92, s[26:27]
	v_cmp_gt_u32_e64 s[24:25], v98, v76
	v_addc_co_u32_e64 v92, s[30:31], 0, v92, s[20:21]
	v_cmp_gt_u32_e64 s[26:27], v99, v76
	v_addc_co_u32_e64 v92, s[30:31], 0, v92, s[22:23]
	ds_read_b128 v[96:99], v58 offset:1120
	s_waitcnt lgkmcnt(1)
	v_cmp_gt_u32_e64 s[20:21], v60, v76
	v_addc_co_u32_e64 v92, s[30:31], 0, v92, s[24:25]
	v_cmp_gt_u32_e64 s[22:23], v61, v76
	v_addc_co_u32_e64 v92, s[30:31], 0, v92, s[26:27]
	v_cmp_gt_u32_e64 s[24:25], v62, v76
	v_addc_co_u32_e64 v92, s[30:31], 0, v92, s[20:21]
	v_cmp_gt_u32_e64 s[26:27], v63, v76
	v_addc_co_u32_e64 v92, s[30:31], 0, v92, s[22:23]
	ds_read_b128 v[60:63], v58 offset:1136
	s_waitcnt lgkmcnt(1)
	v_cmp_gt_u32_e64 s[20:21], v96, v76
	v_addc_co_u32_e64 v92, s[30:31], 0, v92, s[24:25]
	v_cmp_gt_u32_e64 s[22:23], v97, v76
	v_addc_co_u32_e64 v92, s[30:31], 0, v92, s[26:27]
	v_cmp_gt_u32_e64 s[24:25], v98, v76
	v_addc_co_u32_e64 v92, s[30:31], 0, v92, s[20:21]
	v_cmp_gt_u32_e64 s[26:27], v99, v76
	v_addc_co_u32_e64 v92, s[30:31], 0, v92, s[22:23]
	ds_read_b128 v[96:99], v58 offset:1152
	s_waitcnt lgkmcnt(1)
	v_cmp_gt_u32_e64 s[20:21], v60, v76
	v_addc_co_u32_e64 v92, s[30:31], 0, v92, s[24:25]
	v_cmp_gt_u32_e64 s[22:23], v61, v76
	v_addc_co_u32_e64 v92, s[30:31], 0, v92, s[26:27]
	v_cmp_gt_u32_e64 s[24:25], v62, v76
	v_addc_co_u32_e64 v92, s[30:31], 0, v92, s[20:21]
	v_cmp_gt_u32_e64 s[26:27], v63, v76
	v_addc_co_u32_e64 v92, s[30:31], 0, v92, s[22:23]
	ds_read_b128 v[60:63], v58 offset:1168
	s_waitcnt lgkmcnt(1)
	v_cmp_gt_u32_e64 s[20:21], v96, v76
	v_addc_co_u32_e64 v92, s[30:31], 0, v92, s[24:25]
	v_cmp_gt_u32_e64 s[22:23], v97, v76
	v_addc_co_u32_e64 v92, s[30:31], 0, v92, s[26:27]
	v_cmp_gt_u32_e64 s[24:25], v98, v76
	v_addc_co_u32_e64 v92, s[30:31], 0, v92, s[20:21]
	v_cmp_gt_u32_e64 s[26:27], v99, v76
	v_addc_co_u32_e64 v92, s[30:31], 0, v92, s[22:23]
	ds_read_b128 v[96:99], v58 offset:1184
	s_waitcnt lgkmcnt(1)
	v_cmp_gt_u32_e64 s[20:21], v60, v76
	v_addc_co_u32_e64 v92, s[30:31], 0, v92, s[24:25]
	v_cmp_gt_u32_e64 s[22:23], v61, v76
	v_addc_co_u32_e64 v92, s[30:31], 0, v92, s[26:27]
	v_cmp_gt_u32_e64 s[24:25], v62, v76
	v_addc_co_u32_e64 v92, s[30:31], 0, v92, s[20:21]
	v_cmp_gt_u32_e64 s[26:27], v63, v76
	v_addc_co_u32_e64 v92, s[30:31], 0, v92, s[22:23]
	ds_read_b128 v[60:63], v58 offset:1200
	s_waitcnt lgkmcnt(1)
	v_cmp_gt_u32_e64 s[20:21], v96, v76
	v_addc_co_u32_e64 v92, s[30:31], 0, v92, s[24:25]
	v_cmp_gt_u32_e64 s[22:23], v97, v76
	v_addc_co_u32_e64 v92, s[30:31], 0, v92, s[26:27]
	v_cmp_gt_u32_e64 s[24:25], v98, v76
	v_addc_co_u32_e64 v92, s[30:31], 0, v92, s[20:21]
	v_cmp_gt_u32_e64 s[26:27], v99, v76
	v_addc_co_u32_e64 v92, s[30:31], 0, v92, s[22:23]
	ds_read_b128 v[96:99], v58 offset:1216
	s_waitcnt lgkmcnt(1)
	v_cmp_gt_u32_e64 s[20:21], v60, v76
	v_addc_co_u32_e64 v92, s[30:31], 0, v92, s[24:25]
	v_cmp_gt_u32_e64 s[22:23], v61, v76
	v_addc_co_u32_e64 v92, s[30:31], 0, v92, s[26:27]
	v_cmp_gt_u32_e64 s[24:25], v62, v76
	v_addc_co_u32_e64 v92, s[30:31], 0, v92, s[20:21]
	v_cmp_gt_u32_e64 s[26:27], v63, v76
	v_addc_co_u32_e64 v92, s[30:31], 0, v92, s[22:23]
	s_waitcnt lgkmcnt(0)
	v_cmp_gt_u32_e64 s[20:21], v96, v76
	v_addc_co_u32_e64 v92, s[30:31], 0, v92, s[24:25]
	v_cmp_gt_u32_e64 s[22:23], v97, v76
	v_addc_co_u32_e64 v92, s[30:31], 0, v92, s[26:27]
	v_addc_co_u32_e64 v92, s[30:31], 0, v92, s[20:21]
	s_nop 1
	v_addc_co_u32_e64 v92, s[30:31], 0, v92, s[22:23]
	ds_read_b128 v[96:99], v58 offset:1280
	ds_read_b128 v[60:63], v58 offset:1296
	s_waitcnt lgkmcnt(1)
	v_cmp_gt_u32_e64 s[20:21], v96, v77
	v_cmp_gt_u32_e64 s[22:23], v97, v77
	v_cmp_gt_u32_e64 s[24:25], v98, v77
	v_addc_co_u32_e64 v93, s[30:31], 0, v93, s[20:21]
	v_cmp_gt_u32_e64 s[26:27], v99, v77
	v_addc_co_u32_e64 v93, s[30:31], 0, v93, s[22:23]
	ds_read_b128 v[96:99], v58 offset:1312
	s_waitcnt lgkmcnt(1)
	v_cmp_gt_u32_e64 s[20:21], v60, v77
	v_addc_co_u32_e64 v93, s[30:31], 0, v93, s[24:25]
	v_cmp_gt_u32_e64 s[22:23], v61, v77
	v_addc_co_u32_e64 v93, s[30:31], 0, v93, s[26:27]
	v_cmp_gt_u32_e64 s[24:25], v62, v77
	v_addc_co_u32_e64 v93, s[30:31], 0, v93, s[20:21]
	v_cmp_gt_u32_e64 s[26:27], v63, v77
	v_addc_co_u32_e64 v93, s[30:31], 0, v93, s[22:23]
	ds_read_b128 v[60:63], v58 offset:1328
	s_waitcnt lgkmcnt(1)
	v_cmp_gt_u32_e64 s[20:21], v96, v77
	v_addc_co_u32_e64 v93, s[30:31], 0, v93, s[24:25]
	v_cmp_gt_u32_e64 s[22:23], v97, v77
	v_addc_co_u32_e64 v93, s[30:31], 0, v93, s[26:27]
	v_cmp_gt_u32_e64 s[24:25], v98, v77
	v_addc_co_u32_e64 v93, s[30:31], 0, v93, s[20:21]
	v_cmp_gt_u32_e64 s[26:27], v99, v77
	v_addc_co_u32_e64 v93, s[30:31], 0, v93, s[22:23]
	ds_read_b128 v[96:99], v58 offset:1344
	s_waitcnt lgkmcnt(1)
	v_cmp_gt_u32_e64 s[20:21], v60, v77
	v_addc_co_u32_e64 v93, s[30:31], 0, v93, s[24:25]
	v_cmp_gt_u32_e64 s[22:23], v61, v77
	v_addc_co_u32_e64 v93, s[30:31], 0, v93, s[26:27]
	v_cmp_gt_u32_e64 s[24:25], v62, v77
	v_addc_co_u32_e64 v93, s[30:31], 0, v93, s[20:21]
	v_cmp_gt_u32_e64 s[26:27], v63, v77
	v_addc_co_u32_e64 v93, s[30:31], 0, v93, s[22:23]
	ds_read_b128 v[60:63], v58 offset:1360
	s_waitcnt lgkmcnt(1)
	v_cmp_gt_u32_e64 s[20:21], v96, v77
	v_addc_co_u32_e64 v93, s[30:31], 0, v93, s[24:25]
	v_cmp_gt_u32_e64 s[22:23], v97, v77
	v_addc_co_u32_e64 v93, s[30:31], 0, v93, s[26:27]
	v_cmp_gt_u32_e64 s[24:25], v98, v77
	v_addc_co_u32_e64 v93, s[30:31], 0, v93, s[20:21]
	v_cmp_gt_u32_e64 s[26:27], v99, v77
	v_addc_co_u32_e64 v93, s[30:31], 0, v93, s[22:23]
	ds_read_b128 v[96:99], v58 offset:1376
	s_waitcnt lgkmcnt(1)
	v_cmp_gt_u32_e64 s[20:21], v60, v77
	v_addc_co_u32_e64 v93, s[30:31], 0, v93, s[24:25]
	v_cmp_gt_u32_e64 s[22:23], v61, v77
	v_addc_co_u32_e64 v93, s[30:31], 0, v93, s[26:27]
	v_cmp_gt_u32_e64 s[24:25], v62, v77
	v_addc_co_u32_e64 v93, s[30:31], 0, v93, s[20:21]
	v_cmp_gt_u32_e64 s[26:27], v63, v77
	v_addc_co_u32_e64 v93, s[30:31], 0, v93, s[22:23]
	ds_read_b128 v[60:63], v58 offset:1392
	s_waitcnt lgkmcnt(1)
	v_cmp_gt_u32_e64 s[20:21], v96, v77
	v_addc_co_u32_e64 v93, s[30:31], 0, v93, s[24:25]
	v_cmp_gt_u32_e64 s[22:23], v97, v77
	v_addc_co_u32_e64 v93, s[30:31], 0, v93, s[26:27]
	v_cmp_gt_u32_e64 s[24:25], v98, v77
	v_addc_co_u32_e64 v93, s[30:31], 0, v93, s[20:21]
	v_cmp_gt_u32_e64 s[26:27], v99, v77
	v_addc_co_u32_e64 v93, s[30:31], 0, v93, s[22:23]
	ds_read_b128 v[96:99], v58 offset:1408
	s_waitcnt lgkmcnt(1)
	v_cmp_gt_u32_e64 s[20:21], v60, v77
	v_addc_co_u32_e64 v93, s[30:31], 0, v93, s[24:25]
	v_cmp_gt_u32_e64 s[22:23], v61, v77
	v_addc_co_u32_e64 v93, s[30:31], 0, v93, s[26:27]
	v_cmp_gt_u32_e64 s[24:25], v62, v77
	v_addc_co_u32_e64 v93, s[30:31], 0, v93, s[20:21]
	v_cmp_gt_u32_e64 s[26:27], v63, v77
	v_addc_co_u32_e64 v93, s[30:31], 0, v93, s[22:23]
	ds_read_b128 v[60:63], v58 offset:1424
	s_waitcnt lgkmcnt(1)
	v_cmp_gt_u32_e64 s[20:21], v96, v77
	v_addc_co_u32_e64 v93, s[30:31], 0, v93, s[24:25]
	v_cmp_gt_u32_e64 s[22:23], v97, v77
	v_addc_co_u32_e64 v93, s[30:31], 0, v93, s[26:27]
	v_cmp_gt_u32_e64 s[24:25], v98, v77
	v_addc_co_u32_e64 v93, s[30:31], 0, v93, s[20:21]
	v_cmp_gt_u32_e64 s[26:27], v99, v77
	v_addc_co_u32_e64 v93, s[30:31], 0, v93, s[22:23]
	ds_read_b128 v[96:99], v58 offset:1440
	s_waitcnt lgkmcnt(1)
	v_cmp_gt_u32_e64 s[20:21], v60, v77
	v_addc_co_u32_e64 v93, s[30:31], 0, v93, s[24:25]
	v_cmp_gt_u32_e64 s[22:23], v61, v77
	v_addc_co_u32_e64 v93, s[30:31], 0, v93, s[26:27]
	v_cmp_gt_u32_e64 s[24:25], v62, v77
	v_addc_co_u32_e64 v93, s[30:31], 0, v93, s[20:21]
	v_cmp_gt_u32_e64 s[26:27], v63, v77
	v_addc_co_u32_e64 v93, s[30:31], 0, v93, s[22:23]
	ds_read_b128 v[60:63], v58 offset:1456
	s_waitcnt lgkmcnt(1)
	v_cmp_gt_u32_e64 s[20:21], v96, v77
	v_addc_co_u32_e64 v93, s[30:31], 0, v93, s[24:25]
	v_cmp_gt_u32_e64 s[22:23], v97, v77
	v_addc_co_u32_e64 v93, s[30:31], 0, v93, s[26:27]
	v_cmp_gt_u32_e64 s[24:25], v98, v77
	v_addc_co_u32_e64 v93, s[30:31], 0, v93, s[20:21]
	v_cmp_gt_u32_e64 s[26:27], v99, v77
	v_addc_co_u32_e64 v93, s[30:31], 0, v93, s[22:23]
	ds_read_b128 v[96:99], v58 offset:1472
	s_waitcnt lgkmcnt(1)
	v_cmp_gt_u32_e64 s[20:21], v60, v77
	v_addc_co_u32_e64 v93, s[30:31], 0, v93, s[24:25]
	v_cmp_gt_u32_e64 s[22:23], v61, v77
	v_addc_co_u32_e64 v93, s[30:31], 0, v93, s[26:27]
	v_cmp_gt_u32_e64 s[24:25], v62, v77
	v_addc_co_u32_e64 v93, s[30:31], 0, v93, s[20:21]
	v_cmp_gt_u32_e64 s[26:27], v63, v77
	v_addc_co_u32_e64 v93, s[30:31], 0, v93, s[22:23]
	s_waitcnt lgkmcnt(0)
	v_cmp_gt_u32_e64 s[20:21], v96, v77
	v_addc_co_u32_e64 v93, s[30:31], 0, v93, s[24:25]
	v_cmp_gt_u32_e64 s[22:23], v97, v77
	v_addc_co_u32_e64 v93, s[30:31], 0, v93, s[26:27]
	v_addc_co_u32_e64 v93, s[30:31], 0, v93, s[20:21]
	s_nop 1
	v_addc_co_u32_e64 v93, s[30:31], 0, v93, s[22:23]
	ds_read_b128 v[96:99], v58 offset:1536
	ds_read_b128 v[60:63], v58 offset:1552
	s_waitcnt lgkmcnt(1)
	v_cmp_gt_u32_e64 s[20:21], v96, v78
	v_cmp_gt_u32_e64 s[22:23], v97, v78
	v_cmp_gt_u32_e64 s[24:25], v98, v78
	v_addc_co_u32_e64 v94, s[30:31], 0, v94, s[20:21]
	v_cmp_gt_u32_e64 s[26:27], v99, v78
	v_addc_co_u32_e64 v94, s[30:31], 0, v94, s[22:23]
	ds_read_b128 v[96:99], v58 offset:1568
	s_waitcnt lgkmcnt(1)
	v_cmp_gt_u32_e64 s[20:21], v60, v78
	v_addc_co_u32_e64 v94, s[30:31], 0, v94, s[24:25]
	v_cmp_gt_u32_e64 s[22:23], v61, v78
	v_addc_co_u32_e64 v94, s[30:31], 0, v94, s[26:27]
	v_cmp_gt_u32_e64 s[24:25], v62, v78
	v_addc_co_u32_e64 v94, s[30:31], 0, v94, s[20:21]
	v_cmp_gt_u32_e64 s[26:27], v63, v78
	v_addc_co_u32_e64 v94, s[30:31], 0, v94, s[22:23]
	ds_read_b128 v[60:63], v58 offset:1584
	s_waitcnt lgkmcnt(1)
	v_cmp_gt_u32_e64 s[20:21], v96, v78
	v_addc_co_u32_e64 v94, s[30:31], 0, v94, s[24:25]
	v_cmp_gt_u32_e64 s[22:23], v97, v78
	v_addc_co_u32_e64 v94, s[30:31], 0, v94, s[26:27]
	v_cmp_gt_u32_e64 s[24:25], v98, v78
	v_addc_co_u32_e64 v94, s[30:31], 0, v94, s[20:21]
	v_cmp_gt_u32_e64 s[26:27], v99, v78
	v_addc_co_u32_e64 v94, s[30:31], 0, v94, s[22:23]
	ds_read_b128 v[96:99], v58 offset:1600
	s_waitcnt lgkmcnt(1)
	v_cmp_gt_u32_e64 s[20:21], v60, v78
	v_addc_co_u32_e64 v94, s[30:31], 0, v94, s[24:25]
	v_cmp_gt_u32_e64 s[22:23], v61, v78
	v_addc_co_u32_e64 v94, s[30:31], 0, v94, s[26:27]
	v_cmp_gt_u32_e64 s[24:25], v62, v78
	v_addc_co_u32_e64 v94, s[30:31], 0, v94, s[20:21]
	v_cmp_gt_u32_e64 s[26:27], v63, v78
	v_addc_co_u32_e64 v94, s[30:31], 0, v94, s[22:23]
	ds_read_b128 v[60:63], v58 offset:1616
	s_waitcnt lgkmcnt(1)
	v_cmp_gt_u32_e64 s[20:21], v96, v78
	v_addc_co_u32_e64 v94, s[30:31], 0, v94, s[24:25]
	v_cmp_gt_u32_e64 s[22:23], v97, v78
	v_addc_co_u32_e64 v94, s[30:31], 0, v94, s[26:27]
	v_cmp_gt_u32_e64 s[24:25], v98, v78
	v_addc_co_u32_e64 v94, s[30:31], 0, v94, s[20:21]
	v_cmp_gt_u32_e64 s[26:27], v99, v78
	v_addc_co_u32_e64 v94, s[30:31], 0, v94, s[22:23]
	ds_read_b128 v[96:99], v58 offset:1632
	s_waitcnt lgkmcnt(1)
	v_cmp_gt_u32_e64 s[20:21], v60, v78
	v_addc_co_u32_e64 v94, s[30:31], 0, v94, s[24:25]
	v_cmp_gt_u32_e64 s[22:23], v61, v78
	v_addc_co_u32_e64 v94, s[30:31], 0, v94, s[26:27]
	v_cmp_gt_u32_e64 s[24:25], v62, v78
	v_addc_co_u32_e64 v94, s[30:31], 0, v94, s[20:21]
	v_cmp_gt_u32_e64 s[26:27], v63, v78
	v_addc_co_u32_e64 v94, s[30:31], 0, v94, s[22:23]
	ds_read_b128 v[60:63], v58 offset:1648
	s_waitcnt lgkmcnt(1)
	v_cmp_gt_u32_e64 s[20:21], v96, v78
	v_addc_co_u32_e64 v94, s[30:31], 0, v94, s[24:25]
	v_cmp_gt_u32_e64 s[22:23], v97, v78
	v_addc_co_u32_e64 v94, s[30:31], 0, v94, s[26:27]
	v_cmp_gt_u32_e64 s[24:25], v98, v78
	v_addc_co_u32_e64 v94, s[30:31], 0, v94, s[20:21]
	v_cmp_gt_u32_e64 s[26:27], v99, v78
	v_addc_co_u32_e64 v94, s[30:31], 0, v94, s[22:23]
	ds_read_b128 v[96:99], v58 offset:1664
	s_waitcnt lgkmcnt(1)
	v_cmp_gt_u32_e64 s[20:21], v60, v78
	v_addc_co_u32_e64 v94, s[30:31], 0, v94, s[24:25]
	v_cmp_gt_u32_e64 s[22:23], v61, v78
	v_addc_co_u32_e64 v94, s[30:31], 0, v94, s[26:27]
	v_cmp_gt_u32_e64 s[24:25], v62, v78
	v_addc_co_u32_e64 v94, s[30:31], 0, v94, s[20:21]
	v_cmp_gt_u32_e64 s[26:27], v63, v78
	v_addc_co_u32_e64 v94, s[30:31], 0, v94, s[22:23]
	ds_read_b128 v[60:63], v58 offset:1680
	s_waitcnt lgkmcnt(1)
	v_cmp_gt_u32_e64 s[20:21], v96, v78
	v_addc_co_u32_e64 v94, s[30:31], 0, v94, s[24:25]
	v_cmp_gt_u32_e64 s[22:23], v97, v78
	v_addc_co_u32_e64 v94, s[30:31], 0, v94, s[26:27]
	v_cmp_gt_u32_e64 s[24:25], v98, v78
	v_addc_co_u32_e64 v94, s[30:31], 0, v94, s[20:21]
	v_cmp_gt_u32_e64 s[26:27], v99, v78
	v_addc_co_u32_e64 v94, s[30:31], 0, v94, s[22:23]
	ds_read_b128 v[96:99], v58 offset:1696
	s_waitcnt lgkmcnt(1)
	v_cmp_gt_u32_e64 s[20:21], v60, v78
	v_addc_co_u32_e64 v94, s[30:31], 0, v94, s[24:25]
	v_cmp_gt_u32_e64 s[22:23], v61, v78
	v_addc_co_u32_e64 v94, s[30:31], 0, v94, s[26:27]
	v_cmp_gt_u32_e64 s[24:25], v62, v78
	v_addc_co_u32_e64 v94, s[30:31], 0, v94, s[20:21]
	v_cmp_gt_u32_e64 s[26:27], v63, v78
	v_addc_co_u32_e64 v94, s[30:31], 0, v94, s[22:23]
	ds_read_b128 v[60:63], v58 offset:1712
	s_waitcnt lgkmcnt(1)
	v_cmp_gt_u32_e64 s[20:21], v96, v78
	v_addc_co_u32_e64 v94, s[30:31], 0, v94, s[24:25]
	v_cmp_gt_u32_e64 s[22:23], v97, v78
	v_addc_co_u32_e64 v94, s[30:31], 0, v94, s[26:27]
	v_cmp_gt_u32_e64 s[24:25], v98, v78
	v_addc_co_u32_e64 v94, s[30:31], 0, v94, s[20:21]
	v_cmp_gt_u32_e64 s[26:27], v99, v78
	v_addc_co_u32_e64 v94, s[30:31], 0, v94, s[22:23]
	ds_read_b128 v[96:99], v58 offset:1728
	s_waitcnt lgkmcnt(1)
	v_cmp_gt_u32_e64 s[20:21], v60, v78
	v_addc_co_u32_e64 v94, s[30:31], 0, v94, s[24:25]
	v_cmp_gt_u32_e64 s[22:23], v61, v78
	v_addc_co_u32_e64 v94, s[30:31], 0, v94, s[26:27]
	v_cmp_gt_u32_e64 s[24:25], v62, v78
	v_addc_co_u32_e64 v94, s[30:31], 0, v94, s[20:21]
	v_cmp_gt_u32_e64 s[26:27], v63, v78
	v_addc_co_u32_e64 v94, s[30:31], 0, v94, s[22:23]
	s_waitcnt lgkmcnt(0)
	v_cmp_gt_u32_e64 s[20:21], v96, v78
	v_addc_co_u32_e64 v94, s[30:31], 0, v94, s[24:25]
	v_cmp_gt_u32_e64 s[22:23], v97, v78
	v_addc_co_u32_e64 v94, s[30:31], 0, v94, s[26:27]
	v_addc_co_u32_e64 v94, s[30:31], 0, v94, s[20:21]
	s_nop 1
	v_addc_co_u32_e64 v94, s[30:31], 0, v94, s[22:23]
	ds_read_b128 v[96:99], v58 offset:1792
	ds_read_b128 v[60:63], v58 offset:1808
	s_waitcnt lgkmcnt(1)
	v_cmp_gt_u32_e64 s[20:21], v96, v79
	v_cmp_gt_u32_e64 s[22:23], v97, v79
	v_cmp_gt_u32_e64 s[24:25], v98, v79
	v_addc_co_u32_e64 v95, s[30:31], 0, v95, s[20:21]
	v_cmp_gt_u32_e64 s[26:27], v99, v79
	v_addc_co_u32_e64 v95, s[30:31], 0, v95, s[22:23]
	ds_read_b128 v[96:99], v58 offset:1824
	s_waitcnt lgkmcnt(1)
	v_cmp_gt_u32_e64 s[20:21], v60, v79
	v_addc_co_u32_e64 v95, s[30:31], 0, v95, s[24:25]
	v_cmp_gt_u32_e64 s[22:23], v61, v79
	v_addc_co_u32_e64 v95, s[30:31], 0, v95, s[26:27]
	v_cmp_gt_u32_e64 s[24:25], v62, v79
	v_addc_co_u32_e64 v95, s[30:31], 0, v95, s[20:21]
	v_cmp_gt_u32_e64 s[26:27], v63, v79
	v_addc_co_u32_e64 v95, s[30:31], 0, v95, s[22:23]
	ds_read_b128 v[60:63], v58 offset:1840
	s_waitcnt lgkmcnt(1)
	v_cmp_gt_u32_e64 s[20:21], v96, v79
	v_addc_co_u32_e64 v95, s[30:31], 0, v95, s[24:25]
	v_cmp_gt_u32_e64 s[22:23], v97, v79
	v_addc_co_u32_e64 v95, s[30:31], 0, v95, s[26:27]
	v_cmp_gt_u32_e64 s[24:25], v98, v79
	v_addc_co_u32_e64 v95, s[30:31], 0, v95, s[20:21]
	v_cmp_gt_u32_e64 s[26:27], v99, v79
	v_addc_co_u32_e64 v95, s[30:31], 0, v95, s[22:23]
	ds_read_b128 v[96:99], v58 offset:1856
	s_waitcnt lgkmcnt(1)
	v_cmp_gt_u32_e64 s[20:21], v60, v79
	v_addc_co_u32_e64 v95, s[30:31], 0, v95, s[24:25]
	v_cmp_gt_u32_e64 s[22:23], v61, v79
	v_addc_co_u32_e64 v95, s[30:31], 0, v95, s[26:27]
	v_cmp_gt_u32_e64 s[24:25], v62, v79
	v_addc_co_u32_e64 v95, s[30:31], 0, v95, s[20:21]
	v_cmp_gt_u32_e64 s[26:27], v63, v79
	v_addc_co_u32_e64 v95, s[30:31], 0, v95, s[22:23]
	ds_read_b128 v[60:63], v58 offset:1872
	s_waitcnt lgkmcnt(1)
	v_cmp_gt_u32_e64 s[20:21], v96, v79
	v_addc_co_u32_e64 v95, s[30:31], 0, v95, s[24:25]
	v_cmp_gt_u32_e64 s[22:23], v97, v79
	v_addc_co_u32_e64 v95, s[30:31], 0, v95, s[26:27]
	v_cmp_gt_u32_e64 s[24:25], v98, v79
	v_addc_co_u32_e64 v95, s[30:31], 0, v95, s[20:21]
	v_cmp_gt_u32_e64 s[26:27], v99, v79
	v_addc_co_u32_e64 v95, s[30:31], 0, v95, s[22:23]
	ds_read_b128 v[96:99], v58 offset:1888
	s_waitcnt lgkmcnt(1)
	v_cmp_gt_u32_e64 s[20:21], v60, v79
	v_addc_co_u32_e64 v95, s[30:31], 0, v95, s[24:25]
	v_cmp_gt_u32_e64 s[22:23], v61, v79
	v_addc_co_u32_e64 v95, s[30:31], 0, v95, s[26:27]
	v_cmp_gt_u32_e64 s[24:25], v62, v79
	v_addc_co_u32_e64 v95, s[30:31], 0, v95, s[20:21]
	v_cmp_gt_u32_e64 s[26:27], v63, v79
	v_addc_co_u32_e64 v95, s[30:31], 0, v95, s[22:23]
	ds_read_b128 v[60:63], v58 offset:1904
	s_waitcnt lgkmcnt(1)
	v_cmp_gt_u32_e64 s[20:21], v96, v79
	v_addc_co_u32_e64 v95, s[30:31], 0, v95, s[24:25]
	v_cmp_gt_u32_e64 s[22:23], v97, v79
	v_addc_co_u32_e64 v95, s[30:31], 0, v95, s[26:27]
	v_cmp_gt_u32_e64 s[24:25], v98, v79
	v_addc_co_u32_e64 v95, s[30:31], 0, v95, s[20:21]
	v_cmp_gt_u32_e64 s[26:27], v99, v79
	v_addc_co_u32_e64 v95, s[30:31], 0, v95, s[22:23]
	ds_read_b128 v[96:99], v58 offset:1920
	s_waitcnt lgkmcnt(1)
	v_cmp_gt_u32_e64 s[20:21], v60, v79
	v_addc_co_u32_e64 v95, s[30:31], 0, v95, s[24:25]
	v_cmp_gt_u32_e64 s[22:23], v61, v79
	v_addc_co_u32_e64 v95, s[30:31], 0, v95, s[26:27]
	v_cmp_gt_u32_e64 s[24:25], v62, v79
	v_addc_co_u32_e64 v95, s[30:31], 0, v95, s[20:21]
	v_cmp_gt_u32_e64 s[26:27], v63, v79
	v_addc_co_u32_e64 v95, s[30:31], 0, v95, s[22:23]
	ds_read_b128 v[60:63], v58 offset:1936
	s_waitcnt lgkmcnt(1)
	v_cmp_gt_u32_e64 s[20:21], v96, v79
	v_addc_co_u32_e64 v95, s[30:31], 0, v95, s[24:25]
	v_cmp_gt_u32_e64 s[22:23], v97, v79
	v_addc_co_u32_e64 v95, s[30:31], 0, v95, s[26:27]
	v_cmp_gt_u32_e64 s[24:25], v98, v79
	v_addc_co_u32_e64 v95, s[30:31], 0, v95, s[20:21]
	v_cmp_gt_u32_e64 s[26:27], v99, v79
	v_addc_co_u32_e64 v95, s[30:31], 0, v95, s[22:23]
	ds_read_b128 v[96:99], v58 offset:1952
	s_waitcnt lgkmcnt(1)
	v_cmp_gt_u32_e64 s[20:21], v60, v79
	v_addc_co_u32_e64 v95, s[30:31], 0, v95, s[24:25]
	v_cmp_gt_u32_e64 s[22:23], v61, v79
	v_addc_co_u32_e64 v95, s[30:31], 0, v95, s[26:27]
	v_cmp_gt_u32_e64 s[24:25], v62, v79
	v_addc_co_u32_e64 v95, s[30:31], 0, v95, s[20:21]
	v_cmp_gt_u32_e64 s[26:27], v63, v79
	v_addc_co_u32_e64 v95, s[30:31], 0, v95, s[22:23]
	ds_read_b128 v[60:63], v58 offset:1968
	s_waitcnt lgkmcnt(1)
	v_cmp_gt_u32_e64 s[20:21], v96, v79
	v_addc_co_u32_e64 v95, s[30:31], 0, v95, s[24:25]
	v_cmp_gt_u32_e64 s[22:23], v97, v79
	v_addc_co_u32_e64 v95, s[30:31], 0, v95, s[26:27]
	v_cmp_gt_u32_e64 s[24:25], v98, v79
	v_addc_co_u32_e64 v95, s[30:31], 0, v95, s[20:21]
	v_cmp_gt_u32_e64 s[26:27], v99, v79
	v_addc_co_u32_e64 v95, s[30:31], 0, v95, s[22:23]
	ds_read_b128 v[96:99], v58 offset:1984
	s_waitcnt lgkmcnt(1)
	v_cmp_gt_u32_e64 s[20:21], v60, v79
	v_addc_co_u32_e64 v95, s[30:31], 0, v95, s[24:25]
	v_cmp_gt_u32_e64 s[22:23], v61, v79
	v_addc_co_u32_e64 v95, s[30:31], 0, v95, s[26:27]
	v_cmp_gt_u32_e64 s[24:25], v62, v79
	v_addc_co_u32_e64 v95, s[30:31], 0, v95, s[20:21]
	v_cmp_gt_u32_e64 s[26:27], v63, v79
	v_addc_co_u32_e64 v95, s[30:31], 0, v95, s[22:23]
	s_waitcnt lgkmcnt(0)
	v_cmp_gt_u32_e64 s[20:21], v96, v79
	v_addc_co_u32_e64 v95, s[30:31], 0, v95, s[24:25]
	v_cmp_gt_u32_e64 s[22:23], v97, v79
	v_addc_co_u32_e64 v95, s[30:31], 0, v95, s[26:27]
	v_addc_co_u32_e64 v95, s[30:31], 0, v95, s[20:21]
	s_nop 1
	v_addc_co_u32_e64 v95, s[30:31], 0, v95, s[22:23]
	v_cmp_gt_u32_e64 s[20:21], 16, v88
	v_cmp_eq_u32_e64 s[22:23], 0, v88
	v_lshl_add_u32 v63, v88, 4, v174
	s_and_b64 s[20:21], s[20:21], s[34:35]
	s_ff1_i32_b64 s24, s[22:23]
	v_add_u32_e32 v63, 0, v63
	v_readlane_b32 s25, v64, s24
	v_cndmask_b32_e64 v63, v101, v63, s[20:21]
	v_mov_b32_e32 v60, v80
	v_subrev_f32_e32 v61, s25, v64
	v_mul_f32_e32 v61, 0x3fb8aa3b, v61
	v_exp_f32_e32 v61, v61
	s_nop 0
	v_cndmask_b32_e64 v61, 0, v61, s[20:21]
	v_mov_b32_e32 v62, v61
	s_nop 1
	v_add_f32_dpp v62, v62, v62 quad_perm:[1,0,3,2] row_mask:0xf bank_mask:0xf
	s_nop 1
	v_add_f32_dpp v62, v62, v62 quad_perm:[2,3,0,1] row_mask:0xf bank_mask:0xf
	s_nop 1
	v_add_f32_dpp v62, v62, v62 row_half_mirror row_mask:0xf bank_mask:0xf
	s_nop 1
	v_add_f32_dpp v62, v62, v62 row_mirror row_mask:0xf bank_mask:0xf
	v_mov_b32_e32 v100, v62
	s_nop 1
	v_permlane16_swap_b32_e32 v100, v62
	v_add_f32_e32 v62, v62, v100
	v_mov_b32_e32 v100, v62
	s_nop 1
	v_permlane32_swap_b32_e32 v100, v62
	v_add_f32_e32 v62, v62, v100
	v_rcp_f32_e32 v62, v62
	s_nop 0
	v_mul_f32_e32 v61, v61, v62
	ds_write_b64 v63, v[60:61]
	v_cmp_gt_u32_e64 s[20:21], 16, v89
	v_cmp_eq_u32_e64 s[22:23], 0, v89
	v_lshl_add_u32 v63, v89, 4, v174
	s_and_b64 s[20:21], s[20:21], s[34:35]
	s_ff1_i32_b64 s24, s[22:23]
	v_add_u32_e32 v63, 256, v63
	v_readlane_b32 s25, v65, s24
	v_cndmask_b32_e64 v63, v101, v63, s[20:21]
	v_mov_b32_e32 v60, v81
	v_subrev_f32_e32 v61, s25, v65
	v_mul_f32_e32 v61, 0x3fb8aa3b, v61
	v_exp_f32_e32 v61, v61
	s_nop 0
	v_cndmask_b32_e64 v61, 0, v61, s[20:21]
	v_mov_b32_e32 v62, v61
	s_nop 1
	v_add_f32_dpp v62, v62, v62 quad_perm:[1,0,3,2] row_mask:0xf bank_mask:0xf
	s_nop 1
	v_add_f32_dpp v62, v62, v62 quad_perm:[2,3,0,1] row_mask:0xf bank_mask:0xf
	s_nop 1
	v_add_f32_dpp v62, v62, v62 row_half_mirror row_mask:0xf bank_mask:0xf
	s_nop 1
	v_add_f32_dpp v62, v62, v62 row_mirror row_mask:0xf bank_mask:0xf
	v_mov_b32_e32 v100, v62
	s_nop 1
	v_permlane16_swap_b32_e32 v100, v62
	v_add_f32_e32 v62, v62, v100
	v_mov_b32_e32 v100, v62
	s_nop 1
	v_permlane32_swap_b32_e32 v100, v62
	v_add_f32_e32 v62, v62, v100
	v_rcp_f32_e32 v62, v62
	s_nop 0
	v_mul_f32_e32 v61, v61, v62
	ds_write_b64 v63, v[60:61]
	v_cmp_gt_u32_e64 s[20:21], 16, v90
	v_cmp_eq_u32_e64 s[22:23], 0, v90
	v_lshl_add_u32 v63, v90, 4, v174
	s_and_b64 s[20:21], s[20:21], s[34:35]
	s_ff1_i32_b64 s24, s[22:23]
	v_add_u32_e32 v63, 512, v63
	v_readlane_b32 s25, v66, s24
	v_cndmask_b32_e64 v63, v101, v63, s[20:21]
	v_mov_b32_e32 v60, v82
	v_subrev_f32_e32 v61, s25, v66
	v_mul_f32_e32 v61, 0x3fb8aa3b, v61
	v_exp_f32_e32 v61, v61
	s_nop 0
	v_cndmask_b32_e64 v61, 0, v61, s[20:21]
	v_mov_b32_e32 v62, v61
	s_nop 1
	v_add_f32_dpp v62, v62, v62 quad_perm:[1,0,3,2] row_mask:0xf bank_mask:0xf
	s_nop 1
	v_add_f32_dpp v62, v62, v62 quad_perm:[2,3,0,1] row_mask:0xf bank_mask:0xf
	s_nop 1
	v_add_f32_dpp v62, v62, v62 row_half_mirror row_mask:0xf bank_mask:0xf
	s_nop 1
	v_add_f32_dpp v62, v62, v62 row_mirror row_mask:0xf bank_mask:0xf
	v_mov_b32_e32 v100, v62
	s_nop 1
	v_permlane16_swap_b32_e32 v100, v62
	v_add_f32_e32 v62, v62, v100
	v_mov_b32_e32 v100, v62
	s_nop 1
	v_permlane32_swap_b32_e32 v100, v62
	v_add_f32_e32 v62, v62, v100
	v_rcp_f32_e32 v62, v62
	s_nop 0
	v_mul_f32_e32 v61, v61, v62
	ds_write_b64 v63, v[60:61]
	v_cmp_gt_u32_e64 s[20:21], 16, v91
	v_cmp_eq_u32_e64 s[22:23], 0, v91
	v_lshl_add_u32 v63, v91, 4, v174
	s_and_b64 s[20:21], s[20:21], s[34:35]
	s_ff1_i32_b64 s24, s[22:23]
	v_add_u32_e32 v63, 768, v63
	v_readlane_b32 s25, v67, s24
	v_cndmask_b32_e64 v63, v101, v63, s[20:21]
	v_mov_b32_e32 v60, v83
	v_subrev_f32_e32 v61, s25, v67
	v_mul_f32_e32 v61, 0x3fb8aa3b, v61
	v_exp_f32_e32 v61, v61
	s_nop 0
	v_cndmask_b32_e64 v61, 0, v61, s[20:21]
	v_mov_b32_e32 v62, v61
	s_nop 1
	v_add_f32_dpp v62, v62, v62 quad_perm:[1,0,3,2] row_mask:0xf bank_mask:0xf
	s_nop 1
	v_add_f32_dpp v62, v62, v62 quad_perm:[2,3,0,1] row_mask:0xf bank_mask:0xf
	s_nop 1
	v_add_f32_dpp v62, v62, v62 row_half_mirror row_mask:0xf bank_mask:0xf
	s_nop 1
	v_add_f32_dpp v62, v62, v62 row_mirror row_mask:0xf bank_mask:0xf
	v_mov_b32_e32 v100, v62
	s_nop 1
	v_permlane16_swap_b32_e32 v100, v62
	v_add_f32_e32 v62, v62, v100
	v_mov_b32_e32 v100, v62
	s_nop 1
	v_permlane32_swap_b32_e32 v100, v62
	v_add_f32_e32 v62, v62, v100
	v_rcp_f32_e32 v62, v62
	s_nop 0
	v_mul_f32_e32 v61, v61, v62
	ds_write_b64 v63, v[60:61]
	v_cmp_gt_u32_e64 s[20:21], 16, v92
	v_cmp_eq_u32_e64 s[22:23], 0, v92
	v_lshl_add_u32 v63, v92, 4, v174
	s_and_b64 s[20:21], s[20:21], s[34:35]
	s_ff1_i32_b64 s24, s[22:23]
	v_add_u32_e32 v63, 1024, v63
	v_readlane_b32 s25, v68, s24
	v_cndmask_b32_e64 v63, v101, v63, s[20:21]
	v_mov_b32_e32 v60, v84
	v_subrev_f32_e32 v61, s25, v68
	v_mul_f32_e32 v61, 0x3fb8aa3b, v61
	v_exp_f32_e32 v61, v61
	s_nop 0
	v_cndmask_b32_e64 v61, 0, v61, s[20:21]
	v_mov_b32_e32 v62, v61
	s_nop 1
	v_add_f32_dpp v62, v62, v62 quad_perm:[1,0,3,2] row_mask:0xf bank_mask:0xf
	s_nop 1
	v_add_f32_dpp v62, v62, v62 quad_perm:[2,3,0,1] row_mask:0xf bank_mask:0xf
	s_nop 1
	v_add_f32_dpp v62, v62, v62 row_half_mirror row_mask:0xf bank_mask:0xf
	s_nop 1
	v_add_f32_dpp v62, v62, v62 row_mirror row_mask:0xf bank_mask:0xf
	v_mov_b32_e32 v100, v62
	s_nop 1
	v_permlane16_swap_b32_e32 v100, v62
	v_add_f32_e32 v62, v62, v100
	v_mov_b32_e32 v100, v62
	s_nop 1
	v_permlane32_swap_b32_e32 v100, v62
	v_add_f32_e32 v62, v62, v100
	v_rcp_f32_e32 v62, v62
	s_nop 0
	v_mul_f32_e32 v61, v61, v62
	ds_write_b64 v63, v[60:61]
	v_cmp_gt_u32_e64 s[20:21], 16, v93
	v_cmp_eq_u32_e64 s[22:23], 0, v93
	v_lshl_add_u32 v63, v93, 4, v174
	s_and_b64 s[20:21], s[20:21], s[34:35]
	s_ff1_i32_b64 s24, s[22:23]
	v_add_u32_e32 v63, 1280, v63
	v_readlane_b32 s25, v69, s24
	v_cndmask_b32_e64 v63, v101, v63, s[20:21]
	v_mov_b32_e32 v60, v85
	v_subrev_f32_e32 v61, s25, v69
	v_mul_f32_e32 v61, 0x3fb8aa3b, v61
	v_exp_f32_e32 v61, v61
	s_nop 0
	v_cndmask_b32_e64 v61, 0, v61, s[20:21]
	v_mov_b32_e32 v62, v61
	s_nop 1
	v_add_f32_dpp v62, v62, v62 quad_perm:[1,0,3,2] row_mask:0xf bank_mask:0xf
	s_nop 1
	v_add_f32_dpp v62, v62, v62 quad_perm:[2,3,0,1] row_mask:0xf bank_mask:0xf
	s_nop 1
	v_add_f32_dpp v62, v62, v62 row_half_mirror row_mask:0xf bank_mask:0xf
	s_nop 1
	v_add_f32_dpp v62, v62, v62 row_mirror row_mask:0xf bank_mask:0xf
	v_mov_b32_e32 v100, v62
	s_nop 1
	v_permlane16_swap_b32_e32 v100, v62
	v_add_f32_e32 v62, v62, v100
	v_mov_b32_e32 v100, v62
	s_nop 1
	v_permlane32_swap_b32_e32 v100, v62
	v_add_f32_e32 v62, v62, v100
	v_rcp_f32_e32 v62, v62
	s_nop 0
	v_mul_f32_e32 v61, v61, v62
	ds_write_b64 v63, v[60:61]
	v_cmp_gt_u32_e64 s[20:21], 16, v94
	v_cmp_eq_u32_e64 s[22:23], 0, v94
	v_lshl_add_u32 v63, v94, 4, v174
	s_and_b64 s[20:21], s[20:21], s[34:35]
	s_ff1_i32_b64 s24, s[22:23]
	v_add_u32_e32 v63, 1536, v63
	v_readlane_b32 s25, v70, s24
	v_cndmask_b32_e64 v63, v101, v63, s[20:21]
	v_mov_b32_e32 v60, v86
	v_subrev_f32_e32 v61, s25, v70
	v_mul_f32_e32 v61, 0x3fb8aa3b, v61
	v_exp_f32_e32 v61, v61
	s_nop 0
	v_cndmask_b32_e64 v61, 0, v61, s[20:21]
	v_mov_b32_e32 v62, v61
	s_nop 1
	v_add_f32_dpp v62, v62, v62 quad_perm:[1,0,3,2] row_mask:0xf bank_mask:0xf
	s_nop 1
	v_add_f32_dpp v62, v62, v62 quad_perm:[2,3,0,1] row_mask:0xf bank_mask:0xf
	s_nop 1
	v_add_f32_dpp v62, v62, v62 row_half_mirror row_mask:0xf bank_mask:0xf
	s_nop 1
	v_add_f32_dpp v62, v62, v62 row_mirror row_mask:0xf bank_mask:0xf
	v_mov_b32_e32 v100, v62
	s_nop 1
	v_permlane16_swap_b32_e32 v100, v62
	v_add_f32_e32 v62, v62, v100
	v_mov_b32_e32 v100, v62
	s_nop 1
	v_permlane32_swap_b32_e32 v100, v62
	v_add_f32_e32 v62, v62, v100
	v_rcp_f32_e32 v62, v62
	s_nop 0
	v_mul_f32_e32 v61, v61, v62
	ds_write_b64 v63, v[60:61]
	v_cmp_gt_u32_e64 s[20:21], 16, v95
	v_cmp_eq_u32_e64 s[22:23], 0, v95
	v_lshl_add_u32 v63, v95, 4, v174
	s_and_b64 s[20:21], s[20:21], s[34:35]
	s_ff1_i32_b64 s24, s[22:23]
	v_add_u32_e32 v63, 1792, v63
	v_readlane_b32 s25, v71, s24
	v_cndmask_b32_e64 v63, v101, v63, s[20:21]
	v_mov_b32_e32 v60, v87
	v_subrev_f32_e32 v61, s25, v71
	v_mul_f32_e32 v61, 0x3fb8aa3b, v61
	v_exp_f32_e32 v61, v61
	s_nop 0
	v_cndmask_b32_e64 v61, 0, v61, s[20:21]
	v_mov_b32_e32 v62, v61
	s_nop 1
	v_add_f32_dpp v62, v62, v62 quad_perm:[1,0,3,2] row_mask:0xf bank_mask:0xf
	s_nop 1
	v_add_f32_dpp v62, v62, v62 quad_perm:[2,3,0,1] row_mask:0xf bank_mask:0xf
	s_nop 1
	v_add_f32_dpp v62, v62, v62 row_half_mirror row_mask:0xf bank_mask:0xf
	s_nop 1
	v_add_f32_dpp v62, v62, v62 row_mirror row_mask:0xf bank_mask:0xf
	v_mov_b32_e32 v100, v62
	s_nop 1
	v_permlane16_swap_b32_e32 v100, v62
	v_add_f32_e32 v62, v62, v100
	v_mov_b32_e32 v100, v62
	s_nop 1
	v_permlane32_swap_b32_e32 v100, v62
	v_add_f32_e32 v62, v62, v100
	v_rcp_f32_e32 v62, v62
	s_nop 0
	v_mul_f32_e32 v61, v61, v62
	ds_write_b64 v63, v[60:61]
	s_waitcnt lgkmcnt(0)
.LBB0_1944:
	s_waitcnt vmcnt(0) lgkmcnt(0)
	v_readfirstlane_b32 s100, v206
	s_lshr_b32 s100, s100, 6
	s_lshl_b32 s100, s100, 12
	s_add_u32 s100, s100, 0x4000
	v_and_b32_e32 v62, 63, v206
	v_lshl_add_u32 v62, v62, 2, s100
	v_mov_b32_e32 v50, 0
	ds_write_b32 v62, v50
	ds_read_b64 v[52:53], v175
	ds_read_b64 v[54:55], v175 offset:1024
	s_waitcnt lgkmcnt(0)
	v_lshrrev_b32_e32 v56, 8, v52
	v_lshrrev_b32_e32 v57, 8, v54
	v_lshl_add_u32 v56, v56, 2, s100
	v_lshl_add_u32 v57, v57, 2, s100
	v_mov_b32_e32 v50, 1
	ds_add_rtn_u32 v58, v56, v50
	ds_add_rtn_u32 v59, v57, v50
	s_waitcnt lgkmcnt(0)
	ds_read_b32 v60, v62
	s_waitcnt lgkmcnt(0)
	v_mov_b32_e32 v61, v60
	s_nop 1
	v_add_u32_dpp v61, v61, v61 row_shr:1 row_mask:0xf bank_mask:0xf bound_ctrl:1
	s_nop 1
	v_add_u32_dpp v61, v61, v61 row_shr:2 row_mask:0xf bank_mask:0xf bound_ctrl:1
	s_nop 1
	v_add_u32_dpp v61, v61, v61 row_shr:4 row_mask:0xf bank_mask:0xf bound_ctrl:1
	s_nop 1
	v_add_u32_dpp v61, v61, v61 row_shr:8 row_mask:0xf bank_mask:0xf bound_ctrl:1
	s_nop 1
	v_add_u32_dpp v61, v61, v61 row_bcast:15 row_mask:0xa bank_mask:0xf
	s_nop 1
	v_add_u32_dpp v61, v61, v61 row_bcast:31 row_mask:0xc bank_mask:0xf
	s_nop 1
	v_sub_u32_e32 v61, v61, v60
	ds_write_b32 v62, v61
	s_waitcnt lgkmcnt(0)
	ds_read_b32 v60, v56
	ds_read_b32 v61, v57
	s_waitcnt lgkmcnt(0)
	v_add_u32_e32 v58, v58, v60
	v_add_u32_e32 v59, v59, v61
	v_lshl_add_u32 v58, v58, 4, v174
	v_lshl_add_u32 v59, v59, 4, v174
	ds_write_b64 v58, v[52:53]
	ds_write_b64 v59, v[54:55]
	v_pk_add_f32 v[34:35], v[34:35], 1.0 op_sel_hi:[1,0]
	v_pk_add_f32 v[20:21], v[20:21], 1.0 op_sel_hi:[1,0]
	v_pk_fma_f32 v[132:133], v[0:1], v[34:35], v[38:39]
	v_pk_add_f32 v[34:35], v[36:37], 1.0 op_sel_hi:[1,0]
	v_pk_fma_f32 v[136:137], v[4:5], v[20:21], v[24:25]
	v_pk_add_f32 v[20:21], v[22:23], 1.0 op_sel_hi:[1,0]
	v_pk_fma_f32 v[134:135], v[2:3], v[34:35], v[40:41]
	v_pk_fma_f32 v[138:139], v[6:7], v[20:21], v[26:27]
	v_pk_add_f32 v[20:21], v[28:29], 1.0 op_sel_hi:[1,0]
	s_nop 0
	v_pk_fma_f32 v[140:141], v[8:9], v[20:21], v[42:43]
	v_pk_add_f32 v[20:21], v[30:31], 1.0 op_sel_hi:[1,0]
	s_nop 0
	v_pk_fma_f32 v[30:31], v[10:11], v[20:21], v[44:45]
	v_add_f32_e32 v20, 1.0, v46
	v_add_f32_e32 v21, 1.0, v47
	v_fma_f32 v16, v12, v20, v16
	v_add_f32_e32 v20, 1.0, v48
	v_fmac_f32_e32 v17, v13, v21
	v_add_f32_e32 v21, 1.0, v49
	v_pk_fma_f32 v[142:143], v[14:15], v[20:21], v[18:19]
	ds_read_b32 v166, v175
	ds_read_b32 v167, v175 offset:1024
	v_readlane_b32 s0, v251, 40
	v_readlane_b32 s1, v251, 41
	v_readlane_b32 s6, v251, 42
	v_readlane_b32 s7, v251, 43
	v_readfirstlane_b32 s16, v104
	v_readfirstlane_b32 s17, v105
	v_and_b32_e32 v103, 63, v206
	v_lshlrev_b32_e32 v103, 4, v103
	v_and_b32_e32 v169, 3, v206
	v_lshl_add_u32 v169, v169, 4, v174
	s_mov_b32 s2, 0xaaaaaaaa
	s_mov_b32 s3, 0xaaaaaaaa
	s_mov_b32 s4, 0xcccccccc
	s_mov_b32 s5, 0xcccccccc
	s_waitcnt lgkmcnt(0)
	v_lshlrev_b32_e32 v166, 2, v166
	v_lshlrev_b32_e32 v167, 2, v167
	global_load_dword v26, v166, s[0:1]
	global_load_dword v27, v166, s[6:7]
	global_load_dword v28, v167, s[0:1]
	global_load_dword v29, v167, s[6:7]
	ds_read_b32 v148, v169 offset:0
	s_waitcnt lgkmcnt(0)
	v_mov_b32_dpp v182, v148 quad_perm:[0,0,0,0] row_mask:0xf bank_mask:0xf
	v_mov_b32_dpp v183, v148 quad_perm:[1,1,1,1] row_mask:0xf bank_mask:0xf
	v_mov_b32_dpp v184, v148 quad_perm:[2,2,2,2] row_mask:0xf bank_mask:0xf
	v_mov_b32_dpp v125, v148 quad_perm:[3,3,3,3] row_mask:0xf bank_mask:0xf
	v_lshl_add_u32 v182, v182, 11, v103
	v_lshl_add_u32 v183, v183, 11, v103
	v_lshl_add_u32 v184, v184, 11, v103
	v_lshl_add_u32 v125, v125, 11, v103
	global_load_dwordx4 v[34:37], v182, s[16:17]
	global_load_dwordx4 v[42:45], v183, s[16:17]
	global_load_dwordx4 v[50:53], v184, s[16:17]
	global_load_dwordx4 v[58:61], v125, s[16:17]
	global_load_dwordx4 v[38:41], v182, s[16:17] offset:1024
	global_load_dwordx4 v[46:49], v183, s[16:17] offset:1024
	global_load_dwordx4 v[54:57], v184, s[16:17] offset:1024
	global_load_dwordx4 v[62:65], v125, s[16:17] offset:1024
	ds_read_b32 v148, v169 offset:64
	s_waitcnt lgkmcnt(0)
	v_mov_b32_dpp v182, v148 quad_perm:[0,0,0,0] row_mask:0xf bank_mask:0xf
	v_mov_b32_dpp v183, v148 quad_perm:[1,1,1,1] row_mask:0xf bank_mask:0xf
	v_mov_b32_dpp v184, v148 quad_perm:[2,2,2,2] row_mask:0xf bank_mask:0xf
	v_mov_b32_dpp v125, v148 quad_perm:[3,3,3,3] row_mask:0xf bank_mask:0xf
	v_lshl_add_u32 v182, v182, 11, v103
	v_lshl_add_u32 v183, v183, 11, v103
	v_lshl_add_u32 v184, v184, 11, v103
	v_lshl_add_u32 v125, v125, 11, v103
	global_load_dwordx4 v[66:69], v182, s[16:17]
	global_load_dwordx4 v[74:77], v183, s[16:17]
	global_load_dwordx4 v[82:85], v184, s[16:17]
	global_load_dwordx4 v[90:93], v125, s[16:17]
	global_load_dwordx4 v[70:73], v182, s[16:17] offset:1024
	global_load_dwordx4 v[78:81], v183, s[16:17] offset:1024
	global_load_dwordx4 v[86:89], v184, s[16:17] offset:1024
	global_load_dwordx4 v[94:97], v125, s[16:17] offset:1024
	s_waitcnt vmcnt(16)
	ds_write_b64 v175, v[26:27] offset:8
	ds_write_b64 v175, v[28:29] offset:1032
	v_mov_b32_e32 v144, 0
	v_mov_b32_e32 v145, 0
	v_mov_b32_e32 v146, 0
	v_mov_b32_e32 v147, 0
	v_mov_b32_e32 v150, 0
	v_mov_b32_e32 v151, 0
	v_mov_b32_e32 v152, 0
	v_mov_b32_e32 v153, 0
	v_mov_b32_e32 v154, 0
	v_mov_b32_e32 v155, 0
	v_mov_b32_e32 v160, 0
	v_mov_b32_e32 v161, 0
	v_mov_b32_e32 v162, 0
	v_mov_b32_e32 v163, 0
	v_mov_b32_e32 v164, 0
	v_mov_b32_e32 v165, 0
	s_mov_b32 s10, 0
.Lex_loop:
	s_waitcnt vmcnt(12)
	ds_read_b128 v[156:159], v169 offset:0
	v_cvt_pk_f32_fp8_e32 v[18:19], v34
	v_cvt_pk_f32_fp8_e32 v[20:21], v42
	v_cvt_pk_f32_fp8_e32 v[22:23], v50
	v_cvt_pk_f32_fp8_e32 v[24:25], v58
	v_pk_mul_f32 v[26:27], v[18:19], v[132:133]
	v_pk_mul_f32 v[28:29], v[20:21], v[132:133]
	v_pk_mul_f32 v[98:99], v[22:23], v[132:133]
	v_pk_mul_f32 v[100:101], v[24:25], v[132:133]
	v_cvt_pk_f32_fp8_sdwa v[18:19], v34 src0_sel:WORD_1
	v_cvt_pk_f32_fp8_sdwa v[20:21], v42 src0_sel:WORD_1
	v_cvt_pk_f32_fp8_sdwa v[22:23], v50 src0_sel:WORD_1
	v_cvt_pk_f32_fp8_sdwa v[24:25], v58 src0_sel:WORD_1
	v_pk_fma_f32 v[26:27], v[18:19], v[134:135], v[26:27]
	v_pk_fma_f32 v[28:29], v[20:21], v[134:135], v[28:29]
	v_pk_fma_f32 v[98:99], v[22:23], v[134:135], v[98:99]
	v_pk_fma_f32 v[100:101], v[24:25], v[134:135], v[100:101]
	v_cvt_pk_f32_fp8_e32 v[18:19], v35
	v_cvt_pk_f32_fp8_e32 v[20:21], v43
	v_cvt_pk_f32_fp8_e32 v[22:23], v51
	v_cvt_pk_f32_fp8_e32 v[24:25], v59
	v_pk_fma_f32 v[26:27], v[18:19], v[136:137], v[26:27]
	v_pk_fma_f32 v[28:29], v[20:21], v[136:137], v[28:29]
	v_pk_fma_f32 v[98:99], v[22:23], v[136:137], v[98:99]
	v_pk_fma_f32 v[100:101], v[24:25], v[136:137], v[100:101]
	v_cvt_pk_f32_fp8_sdwa v[18:19], v35 src0_sel:WORD_1
	v_cvt_pk_f32_fp8_sdwa v[20:21], v43 src0_sel:WORD_1
	v_cvt_pk_f32_fp8_sdwa v[22:23], v51 src0_sel:WORD_1
	v_cvt_pk_f32_fp8_sdwa v[24:25], v59 src0_sel:WORD_1
	v_pk_fma_f32 v[26:27], v[18:19], v[138:139], v[26:27]
	v_pk_fma_f32 v[28:29], v[20:21], v[138:139], v[28:29]
	v_pk_fma_f32 v[98:99], v[22:23], v[138:139], v[98:99]
	v_pk_fma_f32 v[100:101], v[24:25], v[138:139], v[100:101]
	v_cvt_pk_f32_fp8_e32 v[18:19], v36
	v_cvt_pk_f32_fp8_e32 v[20:21], v44
	v_cvt_pk_f32_fp8_e32 v[22:23], v52
	v_cvt_pk_f32_fp8_e32 v[24:25], v60
	v_pk_fma_f32 v[26:27], v[18:19], v[140:141], v[26:27]
	v_pk_fma_f32 v[28:29], v[20:21], v[140:141], v[28:29]
	v_pk_fma_f32 v[98:99], v[22:23], v[140:141], v[98:99]
	v_pk_fma_f32 v[100:101], v[24:25], v[140:141], v[100:101]
	v_cvt_pk_f32_fp8_sdwa v[18:19], v36 src0_sel:WORD_1
	v_cvt_pk_f32_fp8_sdwa v[20:21], v44 src0_sel:WORD_1
	v_cvt_pk_f32_fp8_sdwa v[22:23], v52 src0_sel:WORD_1
	v_cvt_pk_f32_fp8_sdwa v[24:25], v60 src0_sel:WORD_1
	v_pk_fma_f32 v[26:27], v[18:19], v[30:31], v[26:27]
	v_pk_fma_f32 v[28:29], v[20:21], v[30:31], v[28:29]
	v_pk_fma_f32 v[98:99], v[22:23], v[30:31], v[98:99]
	v_pk_fma_f32 v[100:101], v[24:25], v[30:31], v[100:101]
	v_cvt_pk_f32_fp8_e32 v[18:19], v37
	v_cvt_pk_f32_fp8_e32 v[20:21], v45
	v_cvt_pk_f32_fp8_e32 v[22:23], v53
	v_cvt_pk_f32_fp8_e32 v[24:25], v61
	v_pk_fma_f32 v[26:27], v[18:19], v[16:17], v[26:27]
	v_pk_fma_f32 v[28:29], v[20:21], v[16:17], v[28:29]
	v_pk_fma_f32 v[98:99], v[22:23], v[16:17], v[98:99]
	v_pk_fma_f32 v[100:101], v[24:25], v[16:17], v[100:101]
	v_cvt_pk_f32_fp8_sdwa v[18:19], v37 src0_sel:WORD_1
	v_cvt_pk_f32_fp8_sdwa v[20:21], v45 src0_sel:WORD_1
	v_cvt_pk_f32_fp8_sdwa v[22:23], v53 src0_sel:WORD_1
	v_cvt_pk_f32_fp8_sdwa v[24:25], v61 src0_sel:WORD_1
	v_pk_fma_f32 v[26:27], v[18:19], v[142:143], v[26:27]
	v_pk_fma_f32 v[28:29], v[20:21], v[142:143], v[28:29]
	v_pk_fma_f32 v[98:99], v[22:23], v[142:143], v[98:99]
	v_pk_fma_f32 v[100:101], v[24:25], v[142:143], v[100:101]
	v_add_f32_e32 v26, v26, v27
	v_add_f32_e32 v28, v28, v29
	v_add_f32_e32 v98, v98, v99
	v_add_f32_e32 v100, v100, v101
	s_cmp_eq_u32 s10, 15
	s_cbranch_scc1 .Lex_skipUA
	ds_read_b32 v148, v169 offset:128
	s_waitcnt lgkmcnt(0)
	v_mov_b32_dpp v182, v148 quad_perm:[0,0,0,0] row_mask:0xf bank_mask:0xf
	v_mov_b32_dpp v183, v148 quad_perm:[1,1,1,1] row_mask:0xf bank_mask:0xf
	v_mov_b32_dpp v184, v148 quad_perm:[2,2,2,2] row_mask:0xf bank_mask:0xf
	v_mov_b32_dpp v125, v148 quad_perm:[3,3,3,3] row_mask:0xf bank_mask:0xf
	v_lshl_add_u32 v182, v182, 11, v103
	v_lshl_add_u32 v183, v183, 11, v103
	v_lshl_add_u32 v184, v184, 11, v103
	v_lshl_add_u32 v125, v125, 11, v103
	global_load_dwordx4 v[34:37], v182, s[16:17]
	global_load_dwordx4 v[42:45], v183, s[16:17]
	global_load_dwordx4 v[50:53], v184, s[16:17]
	global_load_dwordx4 v[58:61], v125, s[16:17]
.Lex_skipUA:
	v_cndmask_b32_e64 v166, v26, v28, s[2:3]
	v_cndmask_b32_e64 v167, v28, v26, s[2:3]
	v_cndmask_b32_e64 v168, v98, v100, s[2:3]
	v_cndmask_b32_e64 v27, v100, v98, s[2:3]
	s_nop 0
	v_add_f32_dpp v166, v167, v166 quad_perm:[1,0,3,2] row_mask:0xf bank_mask:0xf
	v_add_f32_dpp v168, v27, v168 quad_perm:[1,0,3,2] row_mask:0xf bank_mask:0xf
	s_nop 0
	v_cndmask_b32_e64 v167, v166, v168, s[4:5]
	v_cndmask_b32_e64 v27, v168, v166, s[4:5]
	s_nop 1
	v_add_f32_dpp v167, v27, v167 quad_perm:[2,3,0,1] row_mask:0xf bank_mask:0xf
	s_nop 1
	v_add_f32_dpp v167, v167, v167 row_ror:4 row_mask:0xf bank_mask:0xf
	s_nop 1
	v_add_f32_dpp v167, v167, v167 row_ror:8 row_mask:0xf bank_mask:0xf
	v_mov_b32_e32 v166, v167
	s_nop 1
	v_permlane16_swap_b32_e32 v166, v167
	v_add_f32_e32 v167, v167, v166
	v_mov_b32_e32 v166, v167
	s_nop 1
	v_permlane32_swap_b32_e32 v166, v167
	v_add_f32_e32 v167, v167, v166
	s_waitcnt lgkmcnt(0)
	v_mul_f32_e32 v167, v158, v167
	v_mul_f32_e32 v149, v167, v167
	v_mul_f32_e32 v149, 0x3d372713, v149
	v_add_f32_e32 v149, 1.0, v149
	v_mul_f32_e32 v149, v167, v149
	v_mul_f32_e32 v149, 0xc0135761, v149
	v_exp_f32_e32 v149, v149
	v_mul_f32_e32 v29, v157, v159
	v_add_f32_e32 v149, 1.0, v149
	v_rcp_f32_e32 v149, v149
	v_mul_f32_e32 v29, v29, v167
	v_mul_f32_e32 v149, v29, v149
	s_nop 1
	v_mov_b32_dpp v170, v149 quad_perm:[0,0,0,0] row_mask:0xf bank_mask:0xf
	v_mov_b32_dpp v171, v149 quad_perm:[1,1,1,1] row_mask:0xf bank_mask:0xf
	v_mov_b32_dpp v172, v149 quad_perm:[2,2,2,2] row_mask:0xf bank_mask:0xf
	v_mov_b32_dpp v173, v149 quad_perm:[3,3,3,3] row_mask:0xf bank_mask:0xf
	s_cmp_eq_u32 s10, 15
	s_cbranch_scc1 .Lex_wxa_last
	s_waitcnt vmcnt(12)
	s_branch .Lex_wxa_go

.Lex_wxa_go:
	v_cvt_pk_f32_fp8_e32 v[18:19], v38
	v_cvt_pk_f32_fp8_sdwa v[20:21], v38 src0_sel:WORD_1
	v_pk_fma_f32 v[144:145], v[18:19], v[170:171], v[144:145] op_sel_hi:[1,0,1]
	v_cvt_pk_f32_fp8_e32 v[22:23], v39
	v_pk_fma_f32 v[146:147], v[20:21], v[170:171], v[146:147] op_sel_hi:[1,0,1]
	v_cvt_pk_f32_fp8_sdwa v[24:25], v39 src0_sel:WORD_1
	v_pk_fma_f32 v[150:151], v[22:23], v[170:171], v[150:151] op_sel_hi:[1,0,1]
	v_cvt_pk_f32_fp8_e32 v[18:19], v40
	v_pk_fma_f32 v[152:153], v[24:25], v[170:171], v[152:153] op_sel_hi:[1,0,1]
	v_cvt_pk_f32_fp8_sdwa v[20:21], v40 src0_sel:WORD_1
	v_pk_fma_f32 v[160:161], v[18:19], v[170:171], v[160:161] op_sel_hi:[1,0,1]
	v_cvt_pk_f32_fp8_e32 v[22:23], v41
	v_pk_fma_f32 v[162:163], v[20:21], v[170:171], v[162:163] op_sel_hi:[1,0,1]
	v_cvt_pk_f32_fp8_sdwa v[24:25], v41 src0_sel:WORD_1
	v_pk_fma_f32 v[164:165], v[22:23], v[170:171], v[164:165] op_sel_hi:[1,0,1]
	v_pk_fma_f32 v[154:155], v[24:25], v[170:171], v[154:155] op_sel_hi:[1,0,1]
	v_cvt_pk_f32_fp8_e32 v[18:19], v46
	v_cvt_pk_f32_fp8_sdwa v[20:21], v46 src0_sel:WORD_1
	v_pk_fma_f32 v[144:145], v[18:19], v[170:171], v[144:145] op_sel:[0,1,0]
	v_cvt_pk_f32_fp8_e32 v[22:23], v47
	v_pk_fma_f32 v[146:147], v[20:21], v[170:171], v[146:147] op_sel:[0,1,0]
	v_cvt_pk_f32_fp8_sdwa v[24:25], v47 src0_sel:WORD_1
	v_pk_fma_f32 v[150:151], v[22:23], v[170:171], v[150:151] op_sel:[0,1,0]
	v_cvt_pk_f32_fp8_e32 v[18:19], v48
	v_pk_fma_f32 v[152:153], v[24:25], v[170:171], v[152:153] op_sel:[0,1,0]
	v_cvt_pk_f32_fp8_sdwa v[20:21], v48 src0_sel:WORD_1
	v_pk_fma_f32 v[160:161], v[18:19], v[170:171], v[160:161] op_sel:[0,1,0]
	v_cvt_pk_f32_fp8_e32 v[22:23], v49
	v_pk_fma_f32 v[162:163], v[20:21], v[170:171], v[162:163] op_sel:[0,1,0]
	v_cvt_pk_f32_fp8_sdwa v[24:25], v49 src0_sel:WORD_1
	v_pk_fma_f32 v[164:165], v[22:23], v[170:171], v[164:165] op_sel:[0,1,0]
	v_pk_fma_f32 v[154:155], v[24:25], v[170:171], v[154:155] op_sel:[0,1,0]
	v_cvt_pk_f32_fp8_e32 v[18:19], v54
	v_cvt_pk_f32_fp8_sdwa v[20:21], v54 src0_sel:WORD_1
	v_pk_fma_f32 v[144:145], v[18:19], v[172:173], v[144:145] op_sel_hi:[1,0,1]
	v_cvt_pk_f32_fp8_e32 v[22:23], v55
	v_pk_fma_f32 v[146:147], v[20:21], v[172:173], v[146:147] op_sel_hi:[1,0,1]
	v_cvt_pk_f32_fp8_sdwa v[24:25], v55 src0_sel:WORD_1
	v_pk_fma_f32 v[150:151], v[22:23], v[172:173], v[150:151] op_sel_hi:[1,0,1]
	v_cvt_pk_f32_fp8_e32 v[18:19], v56
	v_pk_fma_f32 v[152:153], v[24:25], v[172:173], v[152:153] op_sel_hi:[1,0,1]
	v_cvt_pk_f32_fp8_sdwa v[20:21], v56 src0_sel:WORD_1
	v_pk_fma_f32 v[160:161], v[18:19], v[172:173], v[160:161] op_sel_hi:[1,0,1]
	v_cvt_pk_f32_fp8_e32 v[22:23], v57
	v_pk_fma_f32 v[162:163], v[20:21], v[172:173], v[162:163] op_sel_hi:[1,0,1]
	v_cvt_pk_f32_fp8_sdwa v[24:25], v57 src0_sel:WORD_1
	v_pk_fma_f32 v[164:165], v[22:23], v[172:173], v[164:165] op_sel_hi:[1,0,1]
	v_pk_fma_f32 v[154:155], v[24:25], v[172:173], v[154:155] op_sel_hi:[1,0,1]
	v_cvt_pk_f32_fp8_e32 v[18:19], v62
	v_cvt_pk_f32_fp8_sdwa v[20:21], v62 src0_sel:WORD_1
	v_pk_fma_f32 v[144:145], v[18:19], v[172:173], v[144:145] op_sel:[0,1,0]
	v_cvt_pk_f32_fp8_e32 v[22:23], v63
	v_pk_fma_f32 v[146:147], v[20:21], v[172:173], v[146:147] op_sel:[0,1,0]
	v_cvt_pk_f32_fp8_sdwa v[24:25], v63 src0_sel:WORD_1
	v_pk_fma_f32 v[150:151], v[22:23], v[172:173], v[150:151] op_sel:[0,1,0]
	v_cvt_pk_f32_fp8_e32 v[18:19], v64
	v_pk_fma_f32 v[152:153], v[24:25], v[172:173], v[152:153] op_sel:[0,1,0]
	v_cvt_pk_f32_fp8_sdwa v[20:21], v64 src0_sel:WORD_1
	v_pk_fma_f32 v[160:161], v[18:19], v[172:173], v[160:161] op_sel:[0,1,0]
	v_cvt_pk_f32_fp8_e32 v[22:23], v65
	v_pk_fma_f32 v[162:163], v[20:21], v[172:173], v[162:163] op_sel:[0,1,0]
	v_cvt_pk_f32_fp8_sdwa v[24:25], v65 src0_sel:WORD_1
	v_pk_fma_f32 v[164:165], v[22:23], v[172:173], v[164:165] op_sel:[0,1,0]
	v_pk_fma_f32 v[154:155], v[24:25], v[172:173], v[154:155] op_sel:[0,1,0]
	s_cmp_eq_u32 s10, 15
	s_cbranch_scc1 .Lex_skipVA
	global_load_dwordx4 v[38:41], v182, s[16:17] offset:1024
	global_load_dwordx4 v[46:49], v183, s[16:17] offset:1024
	global_load_dwordx4 v[54:57], v184, s[16:17] offset:1024
	global_load_dwordx4 v[62:65], v125, s[16:17] offset:1024
.Lex_skipVA:
	s_cmp_eq_u32 s10, 15
	s_cbranch_scc1 .Lex_wdb_last
	s_waitcnt vmcnt(12)
	s_branch .Lex_wdb_go
.Lex_wdb_last:
	s_waitcnt vmcnt(4)
.Lex_wdb_go:
	ds_read_b128 v[156:159], v169 offset:64
	v_cvt_pk_f32_fp8_e32 v[18:19], v66
	v_cvt_pk_f32_fp8_e32 v[20:21], v74
	v_cvt_pk_f32_fp8_e32 v[22:23], v82
	v_cvt_pk_f32_fp8_e32 v[24:25], v90
	v_pk_mul_f32 v[26:27], v[18:19], v[132:133]
	v_pk_mul_f32 v[28:29], v[20:21], v[132:133]
	v_pk_mul_f32 v[98:99], v[22:23], v[132:133]
	v_pk_mul_f32 v[100:101], v[24:25], v[132:133]
	v_cvt_pk_f32_fp8_sdwa v[18:19], v66 src0_sel:WORD_1
	v_cvt_pk_f32_fp8_sdwa v[20:21], v74 src0_sel:WORD_1
	v_cvt_pk_f32_fp8_sdwa v[22:23], v82 src0_sel:WORD_1
	v_cvt_pk_f32_fp8_sdwa v[24:25], v90 src0_sel:WORD_1
	v_pk_fma_f32 v[26:27], v[18:19], v[134:135], v[26:27]
	v_pk_fma_f32 v[28:29], v[20:21], v[134:135], v[28:29]
	v_pk_fma_f32 v[98:99], v[22:23], v[134:135], v[98:99]
	v_pk_fma_f32 v[100:101], v[24:25], v[134:135], v[100:101]
	v_cvt_pk_f32_fp8_e32 v[18:19], v67
	v_cvt_pk_f32_fp8_e32 v[20:21], v75
	v_cvt_pk_f32_fp8_e32 v[22:23], v83
	v_cvt_pk_f32_fp8_e32 v[24:25], v91
	v_pk_fma_f32 v[26:27], v[18:19], v[136:137], v[26:27]
	v_pk_fma_f32 v[28:29], v[20:21], v[136:137], v[28:29]
	v_pk_fma_f32 v[98:99], v[22:23], v[136:137], v[98:99]
	v_pk_fma_f32 v[100:101], v[24:25], v[136:137], v[100:101]
	v_cvt_pk_f32_fp8_sdwa v[18:19], v67 src0_sel:WORD_1
	v_cvt_pk_f32_fp8_sdwa v[20:21], v75 src0_sel:WORD_1
	v_cvt_pk_f32_fp8_sdwa v[22:23], v83 src0_sel:WORD_1
	v_cvt_pk_f32_fp8_sdwa v[24:25], v91 src0_sel:WORD_1
	v_pk_fma_f32 v[26:27], v[18:19], v[138:139], v[26:27]
	v_pk_fma_f32 v[28:29], v[20:21], v[138:139], v[28:29]
	v_pk_fma_f32 v[98:99], v[22:23], v[138:139], v[98:99]
	v_pk_fma_f32 v[100:101], v[24:25], v[138:139], v[100:101]
	v_cvt_pk_f32_fp8_e32 v[18:19], v68
	v_cvt_pk_f32_fp8_e32 v[20:21], v76
	v_cvt_pk_f32_fp8_e32 v[22:23], v84
	v_cvt_pk_f32_fp8_e32 v[24:25], v92
	v_pk_fma_f32 v[26:27], v[18:19], v[140:141], v[26:27]
	v_pk_fma_f32 v[28:29], v[20:21], v[140:141], v[28:29]
	v_pk_fma_f32 v[98:99], v[22:23], v[140:141], v[98:99]
	v_pk_fma_f32 v[100:101], v[24:25], v[140:141], v[100:101]
	v_cvt_pk_f32_fp8_sdwa v[18:19], v68 src0_sel:WORD_1
	v_cvt_pk_f32_fp8_sdwa v[20:21], v76 src0_sel:WORD_1
	v_cvt_pk_f32_fp8_sdwa v[22:23], v84 src0_sel:WORD_1
	v_cvt_pk_f32_fp8_sdwa v[24:25], v92 src0_sel:WORD_1
	v_pk_fma_f32 v[26:27], v[18:19], v[30:31], v[26:27]
	v_pk_fma_f32 v[28:29], v[20:21], v[30:31], v[28:29]
	v_pk_fma_f32 v[98:99], v[22:23], v[30:31], v[98:99]
	v_pk_fma_f32 v[100:101], v[24:25], v[30:31], v[100:101]
	v_cvt_pk_f32_fp8_e32 v[18:19], v69
	v_cvt_pk_f32_fp8_e32 v[20:21], v77
	v_cvt_pk_f32_fp8_e32 v[22:23], v85
	v_cvt_pk_f32_fp8_e32 v[24:25], v93
	v_pk_fma_f32 v[26:27], v[18:19], v[16:17], v[26:27]
	v_pk_fma_f32 v[28:29], v[20:21], v[16:17], v[28:29]
	v_pk_fma_f32 v[98:99], v[22:23], v[16:17], v[98:99]
	v_pk_fma_f32 v[100:101], v[24:25], v[16:17], v[100:101]
	v_cvt_pk_f32_fp8_sdwa v[18:19], v69 src0_sel:WORD_1
	v_cvt_pk_f32_fp8_sdwa v[20:21], v77 src0_sel:WORD_1
	v_cvt_pk_f32_fp8_sdwa v[22:23], v85 src0_sel:WORD_1
	v_cvt_pk_f32_fp8_sdwa v[24:25], v93 src0_sel:WORD_1
	v_pk_fma_f32 v[26:27], v[18:19], v[142:143], v[26:27]
	v_pk_fma_f32 v[28:29], v[20:21], v[142:143], v[28:29]
	v_pk_fma_f32 v[98:99], v[22:23], v[142:143], v[98:99]
	v_pk_fma_f32 v[100:101], v[24:25], v[142:143], v[100:101]
	v_add_f32_e32 v26, v26, v27
	v_add_f32_e32 v28, v28, v29
	v_add_f32_e32 v98, v98, v99
	v_add_f32_e32 v100, v100, v101
	s_cmp_eq_u32 s10, 15
	s_cbranch_scc1 .Lex_skipUB
	ds_read_b32 v148, v169 offset:192
	s_waitcnt lgkmcnt(0)
	v_mov_b32_dpp v182, v148 quad_perm:[0,0,0,0] row_mask:0xf bank_mask:0xf
	v_mov_b32_dpp v183, v148 quad_perm:[1,1,1,1] row_mask:0xf bank_mask:0xf
	v_mov_b32_dpp v184, v148 quad_perm:[2,2,2,2] row_mask:0xf bank_mask:0xf
	v_mov_b32_dpp v125, v148 quad_perm:[3,3,3,3] row_mask:0xf bank_mask:0xf
	v_lshl_add_u32 v182, v182, 11, v103
	v_lshl_add_u32 v183, v183, 11, v103
	v_lshl_add_u32 v184, v184, 11, v103
	v_lshl_add_u32 v125, v125, 11, v103
	global_load_dwordx4 v[66:69], v182, s[16:17]
	global_load_dwordx4 v[74:77], v183, s[16:17]
	global_load_dwordx4 v[82:85], v184, s[16:17]
	global_load_dwordx4 v[90:93], v125, s[16:17]

.Lex_wxb_go:
	v_cvt_pk_f32_fp8_e32 v[18:19], v70
	v_cvt_pk_f32_fp8_sdwa v[20:21], v70 src0_sel:WORD_1
	v_pk_fma_f32 v[144:145], v[18:19], v[170:171], v[144:145] op_sel_hi:[1,0,1]
	v_cvt_pk_f32_fp8_e32 v[22:23], v71
	v_pk_fma_f32 v[146:147], v[20:21], v[170:171], v[146:147] op_sel_hi:[1,0,1]
	v_cvt_pk_f32_fp8_sdwa v[24:25], v71 src0_sel:WORD_1
	v_pk_fma_f32 v[150:151], v[22:23], v[170:171], v[150:151] op_sel_hi:[1,0,1]
	v_cvt_pk_f32_fp8_e32 v[18:19], v72
	v_pk_fma_f32 v[152:153], v[24:25], v[170:171], v[152:153] op_sel_hi:[1,0,1]
	v_cvt_pk_f32_fp8_sdwa v[20:21], v72 src0_sel:WORD_1
	v_pk_fma_f32 v[160:161], v[18:19], v[170:171], v[160:161] op_sel_hi:[1,0,1]
	v_cvt_pk_f32_fp8_e32 v[22:23], v73
	v_pk_fma_f32 v[162:163], v[20:21], v[170:171], v[162:163] op_sel_hi:[1,0,1]
	v_cvt_pk_f32_fp8_sdwa v[24:25], v73 src0_sel:WORD_1
	v_pk_fma_f32 v[164:165], v[22:23], v[170:171], v[164:165] op_sel_hi:[1,0,1]
	v_pk_fma_f32 v[154:155], v[24:25], v[170:171], v[154:155] op_sel_hi:[1,0,1]
	v_cvt_pk_f32_fp8_e32 v[18:19], v78
	v_cvt_pk_f32_fp8_sdwa v[20:21], v78 src0_sel:WORD_1
	v_pk_fma_f32 v[144:145], v[18:19], v[170:171], v[144:145] op_sel:[0,1,0]
	v_cvt_pk_f32_fp8_e32 v[22:23], v79
	v_pk_fma_f32 v[146:147], v[20:21], v[170:171], v[146:147] op_sel:[0,1,0]
	v_cvt_pk_f32_fp8_sdwa v[24:25], v79 src0_sel:WORD_1
	v_pk_fma_f32 v[150:151], v[22:23], v[170:171], v[150:151] op_sel:[0,1,0]
	v_cvt_pk_f32_fp8_e32 v[18:19], v80
	v_pk_fma_f32 v[152:153], v[24:25], v[170:171], v[152:153] op_sel:[0,1,0]
	v_cvt_pk_f32_fp8_sdwa v[20:21], v80 src0_sel:WORD_1
	v_pk_fma_f32 v[160:161], v[18:19], v[170:171], v[160:161] op_sel:[0,1,0]
	v_cvt_pk_f32_fp8_e32 v[22:23], v81
	v_pk_fma_f32 v[162:163], v[20:21], v[170:171], v[162:163] op_sel:[0,1,0]
	v_cvt_pk_f32_fp8_sdwa v[24:25], v81 src0_sel:WORD_1
	v_pk_fma_f32 v[164:165], v[22:23], v[170:171], v[164:165] op_sel:[0,1,0]
	v_pk_fma_f32 v[154:155], v[24:25], v[170:171], v[154:155] op_sel:[0,1,0]
	v_cvt_pk_f32_fp8_e32 v[18:19], v86
	v_cvt_pk_f32_fp8_sdwa v[20:21], v86 src0_sel:WORD_1
	v_pk_fma_f32 v[144:145], v[18:19], v[172:173], v[144:145] op_sel_hi:[1,0,1]
	v_cvt_pk_f32_fp8_e32 v[22:23], v87
	v_pk_fma_f32 v[146:147], v[20:21], v[172:173], v[146:147] op_sel_hi:[1,0,1]
	v_cvt_pk_f32_fp8_sdwa v[24:25], v87 src0_sel:WORD_1
	v_pk_fma_f32 v[150:151], v[22:23], v[172:173], v[150:151] op_sel_hi:[1,0,1]
	v_cvt_pk_f32_fp8_e32 v[18:19], v88
	v_pk_fma_f32 v[152:153], v[24:25], v[172:173], v[152:153] op_sel_hi:[1,0,1]
	v_cvt_pk_f32_fp8_sdwa v[20:21], v88 src0_sel:WORD_1
	v_pk_fma_f32 v[160:161], v[18:19], v[172:173], v[160:161] op_sel_hi:[1,0,1]
	v_cvt_pk_f32_fp8_e32 v[22:23], v89
	v_pk_fma_f32 v[162:163], v[20:21], v[172:173], v[162:163] op_sel_hi:[1,0,1]
	v_cvt_pk_f32_fp8_sdwa v[24:25], v89 src0_sel:WORD_1
	v_pk_fma_f32 v[164:165], v[22:23], v[172:173], v[164:165] op_sel_hi:[1,0,1]
	v_pk_fma_f32 v[154:155], v[24:25], v[172:173], v[154:155] op_sel_hi:[1,0,1]
	v_cvt_pk_f32_fp8_e32 v[18:19], v94
	v_cvt_pk_f32_fp8_sdwa v[20:21], v94 src0_sel:WORD_1
	v_pk_fma_f32 v[144:145], v[18:19], v[172:173], v[144:145] op_sel:[0,1,0]
	v_cvt_pk_f32_fp8_e32 v[22:23], v95
	v_pk_fma_f32 v[146:147], v[20:21], v[172:173], v[146:147] op_sel:[0,1,0]
	v_cvt_pk_f32_fp8_sdwa v[24:25], v95 src0_sel:WORD_1
	v_pk_fma_f32 v[150:151], v[22:23], v[172:173], v[150:151] op_sel:[0,1,0]
	v_cvt_pk_f32_fp8_e32 v[18:19], v96
	v_pk_fma_f32 v[152:153], v[24:25], v[172:173], v[152:153] op_sel:[0,1,0]
	v_cvt_pk_f32_fp8_sdwa v[20:21], v96 src0_sel:WORD_1
	v_pk_fma_f32 v[160:161], v[18:19], v[172:173], v[160:161] op_sel:[0,1,0]
	v_cvt_pk_f32_fp8_e32 v[22:23], v97
	v_pk_fma_f32 v[162:163], v[20:21], v[172:173], v[162:163] op_sel:[0,1,0]
	v_cvt_pk_f32_fp8_sdwa v[24:25], v97 src0_sel:WORD_1
	v_pk_fma_f32 v[164:165], v[22:23], v[172:173], v[164:165] op_sel:[0,1,0]
	v_pk_fma_f32 v[154:155], v[24:25], v[172:173], v[154:155] op_sel:[0,1,0]
	s_cmp_eq_u32 s10, 15
	s_cbranch_scc1 .Lex_done
	global_load_dwordx4 v[70:73], v182, s[16:17] offset:1024
	global_load_dwordx4 v[78:81], v183, s[16:17] offset:1024
	global_load_dwordx4 v[86:89], v184, s[16:17] offset:1024
	global_load_dwordx4 v[94:97], v125, s[16:17] offset:1024
	v_add_u32_e32 v169, 0x80, v169
	s_add_u32 s10, s10, 1
	s_branch .Lex_loop
